# baseline (speedup 1.0000x reference)
;   DI const char* aptr(const Unit& u) const { return (const char*)(h + (size_t)u.pm * 256 * DM); }
;   DI const char* bptr(const Unit& u) const { return (const char*)(winT + (size_t)u.pn * 256 * DM); }
;   DI bool next(int i, Unit& u) const { const int L = i * G + c; if (L >= nunits) return false; u.kind = 0; decode_unit(L, 65, 32, u.pm, u.pn); return true; }
;   DI const char* aptr(const Unit& u) const { return (const char*)(y + (size_t)u.pm * 256 * DM + (u.pn >> 3) * 512); }
;   DI const char* bptr(const Unit& u) const { return (const char*)(wbT + (size_t)u.pn * 256 * 512); }
;   DI const char* aptr(const Unit& u) const { return (const char*)(h + (size_t)u.pm * 256 * DM); }
;   DI const char* bptr(const Unit& u) const { return (const char*)(wgT + (size_t)u.pn * 64 * DM); }
;   DI const char* aptr(const Unit& u) const { return (const char*)(mixed + (size_t)u.pm * 256 * DM); }
;   DI const char* bptr(const Unit& u) const { return (const char*)(woutT + (size_t)u.pn * 256 * DM); }
; template <class J>
; DI void gemm_phase(LAS unsigned char* lds, const J& job) {
;     ...
;     const bool has_next = job.next(ui + 1, nxt);
;     const char* nA = has_next ? job.aptr(nxt) : cA; const char* nB = has_next ? job.bptr(nxt) : cB;
;     for (int t = 0; t < nt; t += 2) {
;       const bool last = (t == nt - 2);
;       const char* a1 = cA + G_KT(t + 1);
;       const char* a2 = last ? nA + G_KT(0) : cA + G_KT(t + 2); const char* b2 = last ? nB + G_KT(0) : cB + G_KT(t + 2);
;       const char* a3 = last ? nA + G_KT(1) : cA + G_KT(t + 3); const char* b3 = last ? nB + G_KT(1) : cB + G_KT(t + 3);
;     ...
; #pragma unroll
;     for (int a = 0; a < 2; ++a)
; #pragma unroll
;       for (int b = 0; b < 2; ++b)
; #pragma unroll
;         for (int m = 0; m < 4; ++m)
; #pragma unroll
;           for (int n = 0; n < 2; ++n) acc[a][b][m][n] = (f32x4){0.f, 0.f, 0.f, 0.f};
;     cur = nxt; cA = nA; cB = nB; ++ui;
.LBB0_41:
	s_ashr_i32 s21, s20, 31
	s_lshl_b64 s[0:1], s[20:21], 20
	s_add_u32 s62, s10, s0
	s_addc_u32 s63, s11, s1
	s_ashr_i32 s23, s22, 31
	s_lshl_b64 s[0:1], s[22:23], 20
	s_add_u32 s64, s12, s0
	s_addc_u32 s65, s13, s1
	s_add_u32 s21, s70, 0x80000
	s_addc_u32 s23, s71, 0
	s_and_b64 s[0:1], s[72:73], exec
	s_cselect_b32 s4, s62, s70
	s_cselect_b32 s0, s65, s69
	s_cselect_b32 s1, s64, s68
	s_cselect_b32 s2, s63, s71
	s_add_u32 s47, s4, s24
	s_addc_u32 vcc_lo, s2, 0
	s_add_u32 vcc_hi, s1, s24
	s_addc_u32 s33, s0, 0
	s_add_u32 s97, s4, s86
	s_addc_u32 s4, s2, 0
	s_add_u32 s5, s1, s86
	v_mov_b32_e32 v0, 0
	s_addc_u32 s6, s0, 0
	s_mov_b32 s7, -2
	s_mov_b32 s44, s56
	s_mov_b32 s57, s96
	v_mov_b32_e32 v1, v0
	v_mov_b32_e32 v2, v0
	v_mov_b32_e32 v3, v0
	v_mov_b32_e32 v4, v0
	v_mov_b32_e32 v5, v0
	v_mov_b32_e32 v6, v0
	v_mov_b32_e32 v7, v0
	v_mov_b32_e32 v8, v0
	v_mov_b32_e32 v9, v0
	v_mov_b32_e32 v10, v0
	v_mov_b32_e32 v11, v0
	v_mov_b32_e32 v16, v0
	v_mov_b32_e32 v17, v0
	v_mov_b32_e32 v18, v0
	v_mov_b32_e32 v19, v0
	v_mov_b32_e32 v32, v0
	v_mov_b32_e32 v33, v0
	v_mov_b32_e32 v34, v0
	v_mov_b32_e32 v35, v0
	v_mov_b32_e32 v36, v0
	v_mov_b32_e32 v37, v0
	v_mov_b32_e32 v38, v0
	v_mov_b32_e32 v39, v0
	v_mov_b32_e32 v48, v0
	v_mov_b32_e32 v49, v0
	v_mov_b32_e32 v50, v0
	v_mov_b32_e32 v51, v0
	v_mov_b32_e32 v52, v0
	v_mov_b32_e32 v53, v0
	v_mov_b32_e32 v54, v0
	v_mov_b32_e32 v55, v0
	v_mov_b32_e32 v12, v0
	v_mov_b32_e32 v13, v0
	v_mov_b32_e32 v14, v0
	v_mov_b32_e32 v15, v0
	v_mov_b32_e32 v20, v0
	v_mov_b32_e32 v21, v0
	v_mov_b32_e32 v22, v0
	v_mov_b32_e32 v23, v0
	v_mov_b32_e32 v24, v0
	v_mov_b32_e32 v25, v0
	v_mov_b32_e32 v26, v0
	v_mov_b32_e32 v27, v0
	v_mov_b32_e32 v28, v0
	v_mov_b32_e32 v29, v0
	v_mov_b32_e32 v30, v0
	v_mov_b32_e32 v31, v0
	v_mov_b32_e32 v40, v0
	v_mov_b32_e32 v41, v0
	v_mov_b32_e32 v42, v0
	v_mov_b32_e32 v43, v0
	v_mov_b32_e32 v44, v0
	v_mov_b32_e32 v45, v0
	v_mov_b32_e32 v46, v0
	v_mov_b32_e32 v47, v0
	v_mov_b32_e32 v56, v0
	v_mov_b32_e32 v57, v0
	v_mov_b32_e32 v58, v0
	v_mov_b32_e32 v59, v0
	v_mov_b32_e32 v60, v0
	v_mov_b32_e32 v61, v0
	v_mov_b32_e32 v62, v0
	v_mov_b32_e32 v63, v0
	v_mov_b32_e32 v64, v0
	v_mov_b32_e32 v65, v0
	v_mov_b32_e32 v66, v0
	v_mov_b32_e32 v67, v0
	v_mov_b32_e32 v68, v0
	v_mov_b32_e32 v69, v0
	v_mov_b32_e32 v70, v0
	v_mov_b32_e32 v71, v0
	v_mov_b32_e32 v80, v0
	v_mov_b32_e32 v81, v0
	v_mov_b32_e32 v82, v0
	v_mov_b32_e32 v83, v0
	v_mov_b32_e32 v84, v0
	v_mov_b32_e32 v85, v0
	v_mov_b32_e32 v86, v0
	v_mov_b32_e32 v87, v0
	v_mov_b32_e32 v96, v0
	v_mov_b32_e32 v97, v0
	v_mov_b32_e32 v98, v0
	v_mov_b32_e32 v99, v0
	v_mov_b32_e32 v100, v0
	v_mov_b32_e32 v101, v0
	v_mov_b32_e32 v102, v0
	v_mov_b32_e32 v103, v0
	v_mov_b32_e32 v112, v0
	v_mov_b32_e32 v113, v0
	v_mov_b32_e32 v114, v0
	v_mov_b32_e32 v115, v0
	v_mov_b32_e32 v116, v0
	v_mov_b32_e32 v117, v0
	v_mov_b32_e32 v118, v0
	v_mov_b32_e32 v119, v0
	v_mov_b32_e32 v72, v0
	v_mov_b32_e32 v73, v0
	v_mov_b32_e32 v74, v0
	v_mov_b32_e32 v75, v0
	v_mov_b32_e32 v76, v0
	v_mov_b32_e32 v77, v0
	v_mov_b32_e32 v78, v0
	v_mov_b32_e32 v79, v0
	v_mov_b32_e32 v88, v0
	v_mov_b32_e32 v89, v0
	v_mov_b32_e32 v90, v0
	v_mov_b32_e32 v91, v0
	v_mov_b32_e32 v92, v0
	v_mov_b32_e32 v93, v0
	v_mov_b32_e32 v94, v0
	v_mov_b32_e32 v95, v0
	v_mov_b32_e32 v104, v0
	v_mov_b32_e32 v105, v0
	v_mov_b32_e32 v106, v0
	v_mov_b32_e32 v107, v0
	v_mov_b32_e32 v108, v0
	v_mov_b32_e32 v109, v0
	v_mov_b32_e32 v110, v0
	v_mov_b32_e32 v111, v0
	v_mov_b32_e32 v120, v0
	v_mov_b32_e32 v121, v0
	v_mov_b32_e32 v122, v0
	v_mov_b32_e32 v123, v0
	v_mov_b32_e32 v124, v0
	v_mov_b32_e32 v125, v0
	v_mov_b32_e32 v126, v0
	v_mov_b32_e32 v127, v0
	s_add_i32 s1, s57, 0xffffff80
	s_and_b32 s0, s44, 0xf80
	s_and_b32 s1, s1, 0xf00
	s_add_u32 s2, s70, s1
	s_addc_u32 s72, s71, 0
	s_add_u32 s1, s68, s1
	s_addc_u32 s73, s69, 0
	s_and_b32 s74, s57, 0xf80
	s_add_u32 s80, s70, s74
	s_addc_u32 s75, s71, 0
	s_add_u32 s54, s68, s74
	s_addc_u32 s55, s69, 0
	s_cmp_eq_u32 s7, 28
	s_cselect_b32 s77, vcc_lo, s72
	s_cselect_b32 s76, s47, s2
	s_cselect_b32 s79, s33, s73
	s_cselect_b32 s78, vcc_hi, s1
	s_cselect_b32 s75, s4, s75
	s_cselect_b32 s74, s97, s80
	s_cselect_b32 s73, s6, s55
	s_cselect_b32 s72, s5, s54
	s_add_i32 s2, s84, 0x100
	s_add_u32 s0, s21, s0
	s_addc_u32 s1, s23, 0
; #define G_STAGE(bufoff, gbase, voff) do { _Pragma("unroll") for (int _i = 0; _i < 2; ++_i) \
;         __builtin_amdgcn_global_load_lds((const unsigned*)((const char*)(gbase) + (voff)[_i]), (LAS unsigned*)(lds + (bufoff) + ldsw + _i * 8192), 16, 0, 0); } while (0)
; #define G_LDA(dst, b, h) do { _Pragma("unroll") for (int m = 0; m < 4; ++m) _Pragma("unroll") for (int k = 0; k < 2; ++k) dst[m][k] = *(const LAS bf16x8*)(lds + G_SA(b, h) + aoff + m * 2048 + k * 1024); } while (0)
; #define G_LDB(dst, b, h) do { _Pragma("unroll") for (int n = 0; n < 2; ++n) _Pragma("unroll") for (int k = 0; k < 2; ++k) dst[n][k] = *(const LAS bf16x8*)(lds + G_SB(b, h) + boff + n * 2048 + k * 1024); } while (0)
; #define G_MMA(ai, bj, At, Bt) do { __builtin_amdgcn_s_setprio(1); _Pragma("unroll") for (int m = 0; m < 4; ++m) _Pragma("unroll") for (int n = 0; n < 2; ++n) _Pragma("unroll") for (int k = 0; k < 2; ++k) \
;         acc[ai][bj][m][n] = __builtin_amdgcn_mfma_f32_16x16x32_bf16(Bt[n][k], At[m][k], acc[ai][bj][m][n], 0, 0, 0); __builtin_amdgcn_s_setprio(0); } while (0)
; #define G_WAIT_V(n) asm volatile("s_waitcnt vmcnt(" #n ")" ::: "memory")
; #define G_WAIT_L(n) asm volatile("s_waitcnt lgkmcnt(" #n ")" ::: "memory")
; #define G_BAR __builtin_amdgcn_s_barrier()
; #define G_SCHED __builtin_amdgcn_sched_barrier(0)
; template <class J>
; DI void gemm_phase(LAS unsigned char* lds, const J& job) {
;     ...
;       G_LDB(B0, 0, 0); G_SCHED; G_LDA(At, 0, 0); G_STAGE(G_SA(1, 1), a1 + hstepA, voffA);
;       G_WAIT_L(8); G_BAR; G_WAIT_L(0); G_MMA(0, 0, At, B0); G_BAR; G_SCHED;
;       G_LDB(B1, 0, 1); G_STAGE(G_SB(0, 0), b2, voffB);
;       G_BAR; G_WAIT_L(0); G_MMA(0, 1, At, B1); G_BAR;
;       G_LDA(At, 0, 1); G_STAGE(G_SA(0, 0), a2, voffA);
;       G_BAR; G_WAIT_L(0); G_MMA(1, 0, At, B0); G_BAR; G_SCHED;
;       G_STAGE(G_SB(0, 1), b2 + hstepB, voffB);
;       G_WAIT_V(6); G_BAR; G_MMA(1, 1, At, B1); G_BAR;
.LBB0_42:
	ds_read_b128 v[128:131], v221
	ds_read_b128 v[132:135], v221 offset:1024
	ds_read_b128 v[136:139], v221 offset:2048
	ds_read_b128 v[140:143], v221 offset:3072
	s_add_i32 m0, s25, 0xc000
	ds_read_b128 v[154:157], v163
	ds_read_b128 v[164:167], v163 offset:1024
	ds_read_b128 v[168:171], v163 offset:2048
	ds_read_b128 v[172:175], v163 offset:3072
	ds_read_b128 v[176:179], v163 offset:4096
	ds_read_b128 v[180:183], v163 offset:5120
	ds_read_b128 v[184:187], v163 offset:6144
	ds_read_b128 v[188:191], v163 offset:7168
	global_load_lds_dwordx4 v148, s[0:1]
	s_add_i32 m0, s25, 0xe000
	s_nop 0
	global_load_lds_dwordx4 v150, s[0:1]
	s_waitcnt lgkmcnt(8)
	s_barrier
	s_waitcnt lgkmcnt(0)
	v_mfma_f32_16x16x32_bf16 v[124:127], v[128:131], v[154:157], v[124:127]
	v_mfma_f32_16x16x32_bf16 v[120:123], v[136:139], v[154:157], v[120:123]
	v_mfma_f32_16x16x32_bf16 v[108:111], v[128:131], v[168:171], v[108:111]
	v_mfma_f32_16x16x32_bf16 v[104:107], v[136:139], v[168:171], v[104:107]
	v_mfma_f32_16x16x32_bf16 v[92:95], v[128:131], v[176:179], v[92:95]
	v_mfma_f32_16x16x32_bf16 v[88:91], v[136:139], v[176:179], v[88:91]
	v_mfma_f32_16x16x32_bf16 v[76:79], v[128:131], v[184:187], v[76:79]
	v_mfma_f32_16x16x32_bf16 v[72:75], v[136:139], v[184:187], v[72:75]
	v_mfma_f32_16x16x32_bf16 v[124:127], v[132:135], v[164:167], v[124:127]
	v_mfma_f32_16x16x32_bf16 v[120:123], v[140:143], v[164:167], v[120:123]
	v_mfma_f32_16x16x32_bf16 v[108:111], v[132:135], v[172:175], v[108:111]
	v_mfma_f32_16x16x32_bf16 v[104:107], v[140:143], v[172:175], v[104:107]
	v_mfma_f32_16x16x32_bf16 v[92:95], v[132:135], v[180:183], v[92:95]
	v_mfma_f32_16x16x32_bf16 v[88:91], v[140:143], v[180:183], v[88:91]
	v_mfma_f32_16x16x32_bf16 v[76:79], v[132:135], v[188:191], v[76:79]
	v_mfma_f32_16x16x32_bf16 v[72:75], v[140:143], v[188:191], v[72:75]
	s_barrier
	s_add_i32 s54, s85, 0x100
	s_add_i32 s0, s2, s14
	ds_read_b128 v[192:195], v221 offset:16384
	ds_read_b128 v[196:199], v221 offset:17408
	ds_read_b128 v[200:203], v221 offset:18432
	ds_read_b128 v[204:207], v221 offset:19456
	s_mov_b32 m0, s0
	s_nop 0
	global_load_lds_dwordx4 v146, s[78:79]
	s_add_i32 m0, s0, 0x2000
	s_nop 0
	global_load_lds_dwordx4 v152, s[78:79]
	s_barrier
	s_waitcnt lgkmcnt(0)
	v_mfma_f32_16x16x32_bf16 v[116:119], v[192:195], v[154:157], v[116:119]
	v_mfma_f32_16x16x32_bf16 v[112:115], v[200:203], v[154:157], v[112:115]
	v_mfma_f32_16x16x32_bf16 v[100:103], v[192:195], v[168:171], v[100:103]
	v_mfma_f32_16x16x32_bf16 v[96:99], v[200:203], v[168:171], v[96:99]
	v_mfma_f32_16x16x32_bf16 v[84:87], v[192:195], v[176:179], v[84:87]
	v_mfma_f32_16x16x32_bf16 v[80:83], v[200:203], v[176:179], v[80:83]
	v_mfma_f32_16x16x32_bf16 v[68:71], v[192:195], v[184:187], v[68:71]
	v_mfma_f32_16x16x32_bf16 v[64:67], v[200:203], v[184:187], v[64:67]
	v_mfma_f32_16x16x32_bf16 v[116:119], v[196:199], v[164:167], v[116:119]
	v_mfma_f32_16x16x32_bf16 v[112:115], v[204:207], v[164:167], v[112:115]
	v_mfma_f32_16x16x32_bf16 v[100:103], v[196:199], v[172:175], v[100:103]
	v_mfma_f32_16x16x32_bf16 v[96:99], v[204:207], v[172:175], v[96:99]
	v_mfma_f32_16x16x32_bf16 v[84:87], v[196:199], v[180:183], v[84:87]
	v_mfma_f32_16x16x32_bf16 v[80:83], v[204:207], v[180:183], v[80:83]
	v_mfma_f32_16x16x32_bf16 v[68:71], v[196:199], v[188:191], v[68:71]
	v_mfma_f32_16x16x32_bf16 v[64:67], v[204:207], v[188:191], v[64:67]
	s_mov_b32 m0, s25
	s_barrier
	ds_read_b128 v[154:157], v163 offset:16384
	ds_read_b128 v[164:167], v163 offset:17408
	ds_read_b128 v[168:171], v163 offset:18432
	ds_read_b128 v[172:175], v163 offset:19456
	ds_read_b128 v[176:179], v163 offset:20480
	ds_read_b128 v[180:183], v163 offset:21504
	ds_read_b128 v[184:187], v163 offset:22528
	ds_read_b128 v[188:191], v163 offset:23552
	global_load_lds_dwordx4 v148, s[76:77]
	s_mov_b32 m0, s36
	s_nop 0
	global_load_lds_dwordx4 v150, s[76:77]
	s_barrier
	s_waitcnt lgkmcnt(0)
	v_mfma_f32_16x16x32_bf16 v[60:63], v[128:131], v[154:157], v[60:63]
	v_mfma_f32_16x16x32_bf16 v[56:59], v[136:139], v[154:157], v[56:59]
	v_mfma_f32_16x16x32_bf16 v[44:47], v[128:131], v[168:171], v[44:47]
	v_mfma_f32_16x16x32_bf16 v[40:43], v[136:139], v[168:171], v[40:43]
	v_mfma_f32_16x16x32_bf16 v[28:31], v[128:131], v[176:179], v[28:31]
	v_mfma_f32_16x16x32_bf16 v[24:27], v[136:139], v[176:179], v[24:27]
	v_mfma_f32_16x16x32_bf16 v[20:23], v[128:131], v[184:187], v[20:23]
	v_mfma_f32_16x16x32_bf16 v[12:15], v[136:139], v[184:187], v[12:15]
	v_mfma_f32_16x16x32_bf16 v[60:63], v[132:135], v[164:167], v[60:63]
	v_mfma_f32_16x16x32_bf16 v[56:59], v[140:143], v[164:167], v[56:59]
	v_mfma_f32_16x16x32_bf16 v[44:47], v[132:135], v[172:175], v[44:47]
	v_mfma_f32_16x16x32_bf16 v[40:43], v[140:143], v[172:175], v[40:43]
	v_mfma_f32_16x16x32_bf16 v[28:31], v[132:135], v[180:183], v[28:31]
	v_mfma_f32_16x16x32_bf16 v[24:27], v[140:143], v[180:183], v[24:27]
	v_mfma_f32_16x16x32_bf16 v[20:23], v[132:135], v[188:191], v[20:23]
	v_mfma_f32_16x16x32_bf16 v[12:15], v[140:143], v[188:191], v[12:15]
	s_barrier
	s_add_u32 s0, s78, 0x80000
	s_addc_u32 s1, s79, 0
	s_add_i32 s2, s54, s14
	s_mov_b32 m0, s2
	s_nop 0
	global_load_lds_dwordx4 v146, s[0:1]
	s_add_i32 m0, s2, 0x2000
	s_nop 0
	global_load_lds_dwordx4 v152, s[0:1]
	s_waitcnt vmcnt(6)
	s_barrier
; #define G_STAGE(bufoff, gbase, voff) do { _Pragma("unroll") for (int _i = 0; _i < 2; ++_i) \
;         __builtin_amdgcn_global_load_lds((const unsigned*)((const char*)(gbase) + (voff)[_i]), (LAS unsigned*)(lds + (bufoff) + ldsw + _i * 8192), 16, 0, 0); } while (0)
; #define G_LDA(dst, b, h) do { _Pragma("unroll") for (int m = 0; m < 4; ++m) _Pragma("unroll") for (int k = 0; k < 2; ++k) dst[m][k] = *(const LAS bf16x8*)(lds + G_SA(b, h) + aoff + m * 2048 + k * 1024); } while (0)
; #define G_LDB(dst, b, h) do { _Pragma("unroll") for (int n = 0; n < 2; ++n) _Pragma("unroll") for (int k = 0; k < 2; ++k) dst[n][k] = *(const LAS bf16x8*)(lds + G_SB(b, h) + boff + n * 2048 + k * 1024); } while (0)
; #define G_MMA(ai, bj, At, Bt) do { __builtin_amdgcn_s_setprio(1); _Pragma("unroll") for (int m = 0; m < 4; ++m) _Pragma("unroll") for (int n = 0; n < 2; ++n) _Pragma("unroll") for (int k = 0; k < 2; ++k) \
;         acc[ai][bj][m][n] = __builtin_amdgcn_mfma_f32_16x16x32_bf16(Bt[n][k], At[m][k], acc[ai][bj][m][n], 0, 0, 0); __builtin_amdgcn_s_setprio(0); } while (0)
; #define G_WAIT_V(n) asm volatile("s_waitcnt vmcnt(" #n ")" ::: "memory")
; #define G_WAIT_L(n) asm volatile("s_waitcnt lgkmcnt(" #n ")" ::: "memory")
; #define G_BAR __builtin_amdgcn_s_barrier()
; #define G_SCHED __builtin_amdgcn_sched_barrier(0)
; template <class J>
; DI void gemm_phase(LAS unsigned char* lds, const J& job) {
;     ...
;       G_WAIT_V(6); G_BAR; G_MMA(1, 1, At, B1); G_BAR;
;       G_LDB(B0, 1, 0); G_SCHED; G_LDA(At, 1, 0); G_STAGE(G_SA(0, 1), a2 + hstepA, voffA);
;       G_WAIT_L(8); G_BAR; G_WAIT_L(0); G_MMA(0, 0, At, B0); G_BAR; G_SCHED;
;       G_LDB(B1, 1, 1); G_STAGE(G_SB(1, 0), b3, voffB);
;       G_BAR; G_WAIT_L(0); G_MMA(0, 1, At, B1); G_BAR;
;       G_LDA(At, 1, 1); G_STAGE(G_SA(1, 0), a3, voffA);
;       G_BAR; G_WAIT_L(0); G_MMA(1, 0, At, B0); G_BAR; G_SCHED;
	v_mfma_f32_16x16x32_bf16 v[52:55], v[192:195], v[154:157], v[52:55]
	v_mfma_f32_16x16x32_bf16 v[48:51], v[200:203], v[154:157], v[48:51]
	v_mfma_f32_16x16x32_bf16 v[36:39], v[192:195], v[168:171], v[36:39]
	v_mfma_f32_16x16x32_bf16 v[32:35], v[200:203], v[168:171], v[32:35]
	v_mfma_f32_16x16x32_bf16 v[16:19], v[192:195], v[176:179], v[16:19]
	v_mfma_f32_16x16x32_bf16 v[8:11], v[200:203], v[176:179], v[8:11]
	v_mfma_f32_16x16x32_bf16 v[4:7], v[192:195], v[184:187], v[4:7]
	v_mfma_f32_16x16x32_bf16 v[0:3], v[200:203], v[184:187], v[0:3]
	v_mfma_f32_16x16x32_bf16 v[52:55], v[196:199], v[164:167], v[52:55]
	v_mfma_f32_16x16x32_bf16 v[48:51], v[204:207], v[164:167], v[48:51]
	v_mfma_f32_16x16x32_bf16 v[36:39], v[196:199], v[172:175], v[36:39]
	v_mfma_f32_16x16x32_bf16 v[32:35], v[204:207], v[172:175], v[32:35]
	v_mfma_f32_16x16x32_bf16 v[16:19], v[196:199], v[180:183], v[16:19]
	v_mfma_f32_16x16x32_bf16 v[8:11], v[204:207], v[180:183], v[8:11]
	v_mfma_f32_16x16x32_bf16 v[4:7], v[196:199], v[188:191], v[4:7]
	v_mfma_f32_16x16x32_bf16 v[0:3], v[204:207], v[188:191], v[0:3]
	s_add_i32 s2, s88, 0x100
	s_barrier
	ds_read_b128 v[128:131], v221 offset:32768
	ds_read_b128 v[132:135], v221 offset:33792
	ds_read_b128 v[136:139], v221 offset:34816
	ds_read_b128 v[140:143], v221 offset:35840
	s_add_u32 s0, s76, 0x80000
	s_addc_u32 s1, s77, 0
	s_mov_b32 m0, s37
	ds_read_b128 v[154:157], v163 offset:32768
	ds_read_b128 v[164:167], v163 offset:33792
	ds_read_b128 v[168:171], v163 offset:34816
	ds_read_b128 v[172:175], v163 offset:35840
	ds_read_b128 v[176:179], v163 offset:36864
	ds_read_b128 v[180:183], v163 offset:37888
	ds_read_b128 v[184:187], v163 offset:38912
	ds_read_b128 v[188:191], v163 offset:39936
	global_load_lds_dwordx4 v148, s[0:1]
	s_mov_b32 m0, s38
	s_nop 0
	global_load_lds_dwordx4 v150, s[0:1]
	s_waitcnt lgkmcnt(8)
	s_barrier
	s_waitcnt lgkmcnt(0)
	v_mfma_f32_16x16x32_bf16 v[124:127], v[128:131], v[154:157], v[124:127]
	v_mfma_f32_16x16x32_bf16 v[120:123], v[136:139], v[154:157], v[120:123]
	v_mfma_f32_16x16x32_bf16 v[108:111], v[128:131], v[168:171], v[108:111]
	v_mfma_f32_16x16x32_bf16 v[104:107], v[136:139], v[168:171], v[104:107]
	v_mfma_f32_16x16x32_bf16 v[92:95], v[128:131], v[176:179], v[92:95]
	v_mfma_f32_16x16x32_bf16 v[88:91], v[136:139], v[176:179], v[88:91]
	v_mfma_f32_16x16x32_bf16 v[76:79], v[128:131], v[184:187], v[76:79]
	v_mfma_f32_16x16x32_bf16 v[72:75], v[136:139], v[184:187], v[72:75]
	v_mfma_f32_16x16x32_bf16 v[124:127], v[132:135], v[164:167], v[124:127]
	v_mfma_f32_16x16x32_bf16 v[120:123], v[140:143], v[164:167], v[120:123]
	v_mfma_f32_16x16x32_bf16 v[108:111], v[132:135], v[172:175], v[108:111]
	v_mfma_f32_16x16x32_bf16 v[104:107], v[140:143], v[172:175], v[104:107]
	v_mfma_f32_16x16x32_bf16 v[92:95], v[132:135], v[180:183], v[92:95]
	v_mfma_f32_16x16x32_bf16 v[88:91], v[140:143], v[180:183], v[88:91]
	v_mfma_f32_16x16x32_bf16 v[76:79], v[132:135], v[188:191], v[76:79]
	v_mfma_f32_16x16x32_bf16 v[72:75], v[140:143], v[188:191], v[72:75]
	s_barrier
	s_add_i32 s54, s89, 0x100
	s_add_i32 s0, s2, s14
	ds_read_b128 v[192:195], v221 offset:49152
	ds_read_b128 v[196:199], v221 offset:50176
	ds_read_b128 v[200:203], v221 offset:51200
	ds_read_b128 v[204:207], v221 offset:52224
	s_mov_b32 m0, s0
	s_nop 0
	global_load_lds_dwordx4 v146, s[72:73]
	s_add_i32 m0, s0, 0x2000
	s_nop 0
	global_load_lds_dwordx4 v152, s[72:73]
	s_barrier
	s_waitcnt lgkmcnt(0)
	v_mfma_f32_16x16x32_bf16 v[116:119], v[192:195], v[154:157], v[116:119]
	v_mfma_f32_16x16x32_bf16 v[112:115], v[200:203], v[154:157], v[112:115]
	v_mfma_f32_16x16x32_bf16 v[100:103], v[192:195], v[168:171], v[100:103]
	v_mfma_f32_16x16x32_bf16 v[96:99], v[200:203], v[168:171], v[96:99]
	v_mfma_f32_16x16x32_bf16 v[84:87], v[192:195], v[176:179], v[84:87]
	v_mfma_f32_16x16x32_bf16 v[80:83], v[200:203], v[176:179], v[80:83]
	v_mfma_f32_16x16x32_bf16 v[68:71], v[192:195], v[184:187], v[68:71]
	v_mfma_f32_16x16x32_bf16 v[64:67], v[200:203], v[184:187], v[64:67]
	v_mfma_f32_16x16x32_bf16 v[116:119], v[196:199], v[164:167], v[116:119]
	v_mfma_f32_16x16x32_bf16 v[112:115], v[204:207], v[164:167], v[112:115]
	v_mfma_f32_16x16x32_bf16 v[100:103], v[196:199], v[172:175], v[100:103]
	v_mfma_f32_16x16x32_bf16 v[96:99], v[204:207], v[172:175], v[96:99]
	v_mfma_f32_16x16x32_bf16 v[84:87], v[196:199], v[180:183], v[84:87]
	v_mfma_f32_16x16x32_bf16 v[80:83], v[204:207], v[180:183], v[80:83]
	v_mfma_f32_16x16x32_bf16 v[68:71], v[196:199], v[188:191], v[68:71]
	v_mfma_f32_16x16x32_bf16 v[64:67], v[204:207], v[188:191], v[64:67]
	s_mov_b32 m0, s87
	s_barrier
	ds_read_b128 v[154:157], v163 offset:49152
	ds_read_b128 v[164:167], v163 offset:50176
	ds_read_b128 v[168:171], v163 offset:51200
	ds_read_b128 v[172:175], v163 offset:52224
	ds_read_b128 v[176:179], v163 offset:53248
	ds_read_b128 v[180:183], v163 offset:54272
	ds_read_b128 v[184:187], v163 offset:55296
	ds_read_b128 v[188:191], v163 offset:56320
	global_load_lds_dwordx4 v148, s[74:75]
	s_mov_b32 m0, s94
	s_nop 0
	global_load_lds_dwordx4 v150, s[74:75]
	s_barrier
; #define G_STAGE(bufoff, gbase, voff) do { _Pragma("unroll") for (int _i = 0; _i < 2; ++_i) \
;         __builtin_amdgcn_global_load_lds((const unsigned*)((const char*)(gbase) + (voff)[_i]), (LAS unsigned*)(lds + (bufoff) + ldsw + _i * 8192), 16, 0, 0); } while (0)
; #define G_WAIT_V(n) asm volatile("s_waitcnt vmcnt(" #n ")" ::: "memory")
; template <class J>
; DI void gemm_phase(LAS unsigned char* lds, const J& job) {
;     ...
;       const bool last = (t == nt - 2);
;       const char* a1 = cA + G_KT(t + 1);
;       const char* a2 = last ? nA + G_KT(0) : cA + G_KT(t + 2); const char* b2 = last ? nB + G_KT(0) : cB + G_KT(t + 2);
;       const char* a3 = last ? nA + G_KT(1) : cA + G_KT(t + 3); const char* b3 = last ? nB + G_KT(1) : cB + G_KT(t + 3);
;       G_LDB(B0, 0, 0); G_SCHED; G_LDA(At, 0, 0); G_STAGE(G_SA(1, 1), a1 + hstepA, voffA);
;       G_WAIT_L(8); G_BAR; G_WAIT_L(0); G_MMA(0, 0, At, B0); G_BAR; G_SCHED;
;       G_LDB(B1, 0, 1); G_STAGE(G_SB(0, 0), b2, voffB);
;       G_BAR; G_WAIT_L(0); G_MMA(0, 1, At, B1); G_BAR;
;       G_LDA(At, 0, 1); G_STAGE(G_SA(0, 0), a2, voffA);
;       G_BAR; G_WAIT_L(0); G_MMA(1, 0, At, B0); G_BAR; G_SCHED;
;       G_STAGE(G_SB(0, 1), b2 + hstepB, voffB);
;       G_WAIT_V(6); G_BAR; G_MMA(1, 1, At, B1); G_BAR;
;       G_LDB(B0, 1, 0); G_SCHED; G_LDA(At, 1, 0); G_STAGE(G_SA(0, 1), a2 + hstepA, voffA);
;       G_WAIT_L(8); G_BAR; G_WAIT_L(0); G_MMA(0, 0, At, B0); G_BAR; G_SCHED;
;       G_LDB(B1, 1, 1); G_STAGE(G_SB(1, 0), b3, voffB);
;       G_BAR; G_WAIT_L(0); G_MMA(0, 1, At, B1); G_BAR;
;       G_LDA(At, 1, 1); G_STAGE(G_SA(1, 0), a3, voffA);
;       G_BAR; G_WAIT_L(0); G_MMA(1, 0, At, B0); G_BAR; G_SCHED;
;       G_STAGE(G_SB(1, 1), b3 + hstepB, voffB);
;       G_WAIT_V(6); G_BAR; G_MMA(1, 1, At, B1); G_BAR;
;   DI void epi(const Acc& acc, const Unit& u, int wr, int wc, int fr, int fq) const {
; #pragma unroll
;     for (int ai = 0; ai < 2; ++ai) {
;       f32x4 res[4][2][2];
; #pragma unroll
;       for (int m = 0; m < 4; ++m) {
;         const int row = u.pm * 256 + ai * HALF + wr * 64 + m * 16 + fr;
;         const float* src = (l == 0) ? xp + (size_t)row * DM : out + (size_t)row * DM;
; #pragma unroll
;         for (int bj = 0; bj < 2; ++bj) { const int col = u.pn * 256 + bj * HALF + wc * 32 + 8 * fq; res[m][bj][0] = *(const f32x4*)(src + col); res[m][bj][1] = *(const f32x4*)(src + col + 4); }
;       }
	s_waitcnt lgkmcnt(0)
	v_mfma_f32_16x16x32_bf16 v[60:63], v[128:131], v[154:157], v[60:63]
	v_mfma_f32_16x16x32_bf16 v[56:59], v[136:139], v[154:157], v[56:59]
	v_mfma_f32_16x16x32_bf16 v[44:47], v[128:131], v[168:171], v[44:47]
	v_mfma_f32_16x16x32_bf16 v[40:43], v[136:139], v[168:171], v[40:43]
	v_mfma_f32_16x16x32_bf16 v[28:31], v[128:131], v[176:179], v[28:31]
	v_mfma_f32_16x16x32_bf16 v[24:27], v[136:139], v[176:179], v[24:27]
	v_mfma_f32_16x16x32_bf16 v[20:23], v[128:131], v[184:187], v[20:23]
	v_mfma_f32_16x16x32_bf16 v[12:15], v[136:139], v[184:187], v[12:15]
	v_mfma_f32_16x16x32_bf16 v[60:63], v[132:135], v[164:167], v[60:63]
	v_mfma_f32_16x16x32_bf16 v[56:59], v[140:143], v[164:167], v[56:59]
	v_mfma_f32_16x16x32_bf16 v[44:47], v[132:135], v[172:175], v[44:47]
	v_mfma_f32_16x16x32_bf16 v[40:43], v[140:143], v[172:175], v[40:43]
	v_mfma_f32_16x16x32_bf16 v[28:31], v[132:135], v[180:183], v[28:31]
	v_mfma_f32_16x16x32_bf16 v[24:27], v[140:143], v[180:183], v[24:27]
	v_mfma_f32_16x16x32_bf16 v[20:23], v[132:135], v[188:191], v[20:23]
	v_mfma_f32_16x16x32_bf16 v[12:15], v[140:143], v[188:191], v[12:15]
	s_barrier
	s_add_u32 s0, s72, 0x80000
	s_addc_u32 s1, s73, 0
	s_add_i32 s2, s54, s14
	s_mov_b32 m0, s2
	s_nop 0
	global_load_lds_dwordx4 v146, s[0:1]
	s_add_i32 m0, s2, 0x2000
	s_nop 0
	global_load_lds_dwordx4 v152, s[0:1]
	s_add_i32 s7, s7, 2
	s_addk_i32 s57, 0x100
	s_addk_i32 s44, 0x100
	s_add_i32 s1, s57, 0xffffff80
	s_and_b32 s0, s44, 0xf80
	s_and_b32 s1, s1, 0xf00
	s_add_u32 s2, s70, s1
	s_addc_u32 s72, s71, 0
	s_add_u32 s1, s68, s1
	s_addc_u32 s73, s69, 0
	s_and_b32 s74, s57, 0xf80
	s_add_u32 s80, s70, s74
	s_addc_u32 s75, s71, 0
	s_add_u32 s54, s68, s74
	s_addc_u32 s55, s69, 0
	s_cmp_eq_u32 s7, 28
	s_cselect_b32 s77, vcc_lo, s72
	s_cselect_b32 s76, s47, s2
	s_cselect_b32 s79, s33, s73
	s_cselect_b32 s78, vcc_hi, s1
	s_cselect_b32 s75, s4, s75
	s_cselect_b32 s74, s97, s80
	s_cselect_b32 s73, s6, s55
	s_cselect_b32 s72, s5, s54
	s_add_i32 s2, s84, 0x100
	s_add_u32 s0, s21, s0
	s_addc_u32 s1, s23, 0
	s_waitcnt vmcnt(6)
	s_barrier
	v_mfma_f32_16x16x32_bf16 v[52:55], v[192:195], v[154:157], v[52:55]
	v_mfma_f32_16x16x32_bf16 v[48:51], v[200:203], v[154:157], v[48:51]
	v_mfma_f32_16x16x32_bf16 v[36:39], v[192:195], v[168:171], v[36:39]
	v_mfma_f32_16x16x32_bf16 v[32:35], v[200:203], v[168:171], v[32:35]
	v_mfma_f32_16x16x32_bf16 v[16:19], v[192:195], v[176:179], v[16:19]
	v_mfma_f32_16x16x32_bf16 v[8:11], v[200:203], v[176:179], v[8:11]
	v_mfma_f32_16x16x32_bf16 v[4:7], v[192:195], v[184:187], v[4:7]
	v_mfma_f32_16x16x32_bf16 v[0:3], v[200:203], v[184:187], v[0:3]
	v_mfma_f32_16x16x32_bf16 v[52:55], v[196:199], v[164:167], v[52:55]
	v_mfma_f32_16x16x32_bf16 v[48:51], v[204:207], v[164:167], v[48:51]
	v_mfma_f32_16x16x32_bf16 v[36:39], v[196:199], v[172:175], v[36:39]
	v_mfma_f32_16x16x32_bf16 v[32:35], v[204:207], v[172:175], v[32:35]
	v_mfma_f32_16x16x32_bf16 v[16:19], v[196:199], v[180:183], v[16:19]
	v_mfma_f32_16x16x32_bf16 v[8:11], v[204:207], v[180:183], v[8:11]
	v_mfma_f32_16x16x32_bf16 v[4:7], v[196:199], v[188:191], v[4:7]
	v_mfma_f32_16x16x32_bf16 v[0:3], v[204:207], v[188:191], v[0:3]
	s_cmp_gt_u32 s7, 29
	s_barrier
	s_cbranch_scc0 .LBB0_42
	s_lshl_b32 s0, s66, 8
	v_mov_b32_e32 v128, v161
	v_mov_b32_e32 v129, v160
	s_add_i32 s0, s0, s67
	s_and_b64 vcc, exec, s[18:19]
	v_add_u32_e32 v156, s0, v129
	s_lshl_b32 s0, s46, 8
	s_or_b32 s0, s0, s83
	v_lshl_add_u32 v128, v128, 3, s0
	v_ashrrev_i32_e32 v157, 31, v156
	v_ashrrev_i32_e32 v129, 31, v128
	v_lshlrev_b64 v[212:213], 13, v[156:157]
	v_lshl_add_u64 v[130:131], s[8:9], 0, v[212:213]
	v_lshlrev_b64 v[154:155], 2, v[128:129]
	v_lshl_add_u64 v[128:129], v[130:131], 0, v[154:155]
	global_load_dwordx4 v[164:167], v[128:129], off offset:16
	global_load_dwordx4 v[168:171], v[128:129], off
	global_load_dwordx4 v[172:175], v[128:129], off offset:528
	global_load_dwordx4 v[176:179], v[128:129], off offset:512
	v_add_u32_e32 v128, 16, v156
	v_ashrrev_i32_e32 v129, 31, v128
	v_lshlrev_b64 v[214:215], 13, v[128:129]
	v_lshl_add_u64 v[128:129], s[8:9], 0, v[214:215]
	v_lshl_add_u64 v[128:129], v[128:129], 0, v[154:155]
	global_load_dwordx4 v[180:183], v[128:129], off offset:16
	global_load_dwordx4 v[184:187], v[128:129], off
	global_load_dwordx4 v[188:191], v[128:129], off offset:528
	global_load_dwordx4 v[192:195], v[128:129], off offset:512
	v_add_u32_e32 v128, 32, v156
	v_ashrrev_i32_e32 v129, 31, v128
	v_lshlrev_b64 v[216:217], 13, v[128:129]
	v_lshl_add_u64 v[128:129], s[8:9], 0, v[216:217]
	v_lshl_add_u64 v[128:129], v[128:129], 0, v[154:155]
	global_load_dwordx4 v[196:199], v[128:129], off offset:16
	global_load_dwordx4 v[200:203], v[128:129], off
	global_load_dwordx4 v[204:207], v[128:129], off offset:528
	global_load_dwordx4 v[208:211], v[128:129], off offset:512
	v_add_u32_e32 v128, 48, v156
	v_ashrrev_i32_e32 v129, 31, v128
	v_lshlrev_b64 v[158:159], 13, v[128:129]
	v_lshl_add_u64 v[128:129], s[8:9], 0, v[158:159]
	v_lshl_add_u64 v[136:137], v[128:129], 0, v[154:155]
	global_load_dwordx4 v[132:135], v[136:137], off offset:16
	global_load_dwordx4 v[140:143], v[136:137], off
	global_load_dwordx4 v[128:131], v[136:137], off offset:528
	s_nop 0
	global_load_dwordx4 v[136:139], v[136:137], off offset:512
	v_lshl_add_u64 v[212:213], s[16:17], 0, v[212:213]
	s_mov_b32 s46, s22
	s_mov_b32 s66, s20
	s_mov_b64 s[68:69], s[64:65]
	s_mov_b64 s[70:71], s[62:63]
	s_movk_i32 s54, 0x4000
	s_movk_i32 s55, 0x6000
	v_readlane_b32 s0, v255, 23
	s_cmpk_gt_u32 s0, 0xff
	s_cbranch_scc1 .Lds_out_x
	s_barrier

;   DI const char* aptr(const Unit& u) const { return (const char*)(h + (size_t)u.pm * 256 * DM); }
;   DI const char* bptr(const Unit& u) const { return (const char*)(winT + (size_t)u.pn * 256 * DM); }
;   DI bool next(int i, Unit& u) const { const int L = i * G + c; if (L >= nunits) return false; u.kind = 0; decode_unit(L, 65, 32, u.pm, u.pn); return true; }
;   DI const char* aptr(const Unit& u) const { return (const char*)(y + (size_t)u.pm * 256 * DM + (u.pn >> 3) * 512); }
;   DI const char* bptr(const Unit& u) const { return (const char*)(wbT + (size_t)u.pn * 256 * 512); }
;   DI const char* aptr(const Unit& u) const { return (const char*)(h + (size_t)u.pm * 256 * DM); }
;   DI const char* bptr(const Unit& u) const { return (const char*)(wgT + (size_t)u.pn * 64 * DM); }
;   DI const char* aptr(const Unit& u) const { return (const char*)(mixed + (size_t)u.pm * 256 * DM); }
;   DI const char* bptr(const Unit& u) const { return (const char*)(woutT + (size_t)u.pn * 256 * DM); }
; template <class J>
; DI void gemm_phase(LAS unsigned char* lds, const J& job) {
;     ...
;     const bool has_next = job.next(ui + 1, nxt);
;     const char* nA = has_next ? job.aptr(nxt) : cA; const char* nB = has_next ? job.bptr(nxt) : cB;
;     for (int t = 0; t < nt; t += 2) {
;       const bool last = (t == nt - 2);
;       const char* a1 = cA + G_KT(t + 1);
;       const char* a2 = last ? nA + G_KT(0) : cA + G_KT(t + 2); const char* b2 = last ? nB + G_KT(0) : cB + G_KT(t + 2);
;       const char* a3 = last ? nA + G_KT(1) : cA + G_KT(t + 3); const char* b3 = last ? nB + G_KT(1) : cB + G_KT(t + 3);
;     ...
; #pragma unroll
;     for (int a = 0; a < 2; ++a)
; #pragma unroll
;       for (int b = 0; b < 2; ++b)
; #pragma unroll
;         for (int m = 0; m < 4; ++m)
; #pragma unroll
;           for (int n = 0; n < 2; ++n) acc[a][b][m][n] = (f32x4){0.f, 0.f, 0.f, 0.f};
;     cur = nxt; cA = nA; cB = nB; ++ui;
.LBB0_73:
	s_ashr_i32 s19, s18, 31
	s_lshl_b64 s[6:7], s[18:19], 20
	s_add_u32 s22, s58, s6
	s_addc_u32 s23, s59, s7
	s_ashr_i32 s21, s20, 31
	s_lshl_b64 s[6:7], s[20:21], 18
	s_add_u32 s62, s16, s6
	s_addc_u32 s63, s17, s7
	s_add_u32 s19, s68, 0x80000
	s_addc_u32 s21, s69, 0
	s_and_b64 s[6:7], s[70:71], exec
	s_cselect_b32 s6, s22, s68
	s_cselect_b32 s0, s63, s67
	s_cselect_b32 s1, s62, s66
	s_cselect_b32 s5, s23, s69
	s_add_u32 s45, s6, s65
	s_addc_u32 s46, s5, 0
	s_add_u32 s47, s1, s65
	s_addc_u32 vcc_lo, s0, 0
	s_add_u32 s33, s6, s94
	s_addc_u32 s97, s5, 0
	s_add_u32 vcc_hi, s1, s94
	v_mov_b32_e32 v0, 0
	s_addc_u32 s5, s0, 0
	s_mov_b32 s6, -2
	s_mov_b32 s7, s86
	s_mov_b32 s56, s4
	v_mov_b32_e32 v1, v0
	v_mov_b32_e32 v2, v0
	v_mov_b32_e32 v3, v0
	v_mov_b32_e32 v4, v0
	v_mov_b32_e32 v5, v0
	v_mov_b32_e32 v6, v0
	v_mov_b32_e32 v7, v0
	v_mov_b32_e32 v16, v0
	v_mov_b32_e32 v17, v0
	v_mov_b32_e32 v18, v0
	v_mov_b32_e32 v19, v0
	v_mov_b32_e32 v20, v0
	v_mov_b32_e32 v21, v0
	v_mov_b32_e32 v22, v0
	v_mov_b32_e32 v23, v0
	v_mov_b32_e32 v32, v0
	v_mov_b32_e32 v33, v0
	v_mov_b32_e32 v34, v0
	v_mov_b32_e32 v35, v0
	v_mov_b32_e32 v36, v0
	v_mov_b32_e32 v37, v0
	v_mov_b32_e32 v38, v0
	v_mov_b32_e32 v39, v0
	v_mov_b32_e32 v48, v0
	v_mov_b32_e32 v49, v0
	v_mov_b32_e32 v50, v0
	v_mov_b32_e32 v51, v0
	v_mov_b32_e32 v52, v0
	v_mov_b32_e32 v53, v0
	v_mov_b32_e32 v54, v0
	v_mov_b32_e32 v55, v0
	v_mov_b32_e32 v8, v0
	v_mov_b32_e32 v9, v0
	v_mov_b32_e32 v10, v0
	v_mov_b32_e32 v11, v0
	v_mov_b32_e32 v12, v0
	v_mov_b32_e32 v13, v0
	v_mov_b32_e32 v14, v0
	v_mov_b32_e32 v15, v0
	v_mov_b32_e32 v24, v0
	v_mov_b32_e32 v25, v0
	v_mov_b32_e32 v26, v0
	v_mov_b32_e32 v27, v0
	v_mov_b32_e32 v28, v0
	v_mov_b32_e32 v29, v0
	v_mov_b32_e32 v30, v0
	v_mov_b32_e32 v31, v0
	v_mov_b32_e32 v40, v0
	v_mov_b32_e32 v41, v0
	v_mov_b32_e32 v42, v0
	v_mov_b32_e32 v43, v0
	v_mov_b32_e32 v44, v0
	v_mov_b32_e32 v45, v0
	v_mov_b32_e32 v46, v0
	v_mov_b32_e32 v47, v0
	v_mov_b32_e32 v56, v0
	v_mov_b32_e32 v57, v0
	v_mov_b32_e32 v58, v0
	v_mov_b32_e32 v59, v0
	v_mov_b32_e32 v60, v0
	v_mov_b32_e32 v61, v0
	v_mov_b32_e32 v62, v0
	v_mov_b32_e32 v63, v0
	v_mov_b32_e32 v64, v0
	v_mov_b32_e32 v65, v0
	v_mov_b32_e32 v66, v0
	v_mov_b32_e32 v67, v0
	v_mov_b32_e32 v68, v0
	v_mov_b32_e32 v69, v0
	v_mov_b32_e32 v70, v0
	v_mov_b32_e32 v71, v0
	v_mov_b32_e32 v80, v0
	v_mov_b32_e32 v81, v0
	v_mov_b32_e32 v82, v0
	v_mov_b32_e32 v83, v0
	v_mov_b32_e32 v92, v0
	v_mov_b32_e32 v93, v0
	v_mov_b32_e32 v94, v0
	v_mov_b32_e32 v95, v0
	v_mov_b32_e32 v112, v0
	v_mov_b32_e32 v113, v0
	v_mov_b32_e32 v114, v0
	v_mov_b32_e32 v115, v0
	v_mov_b32_e32 v116, v0
	v_mov_b32_e32 v117, v0
	v_mov_b32_e32 v118, v0
	v_mov_b32_e32 v119, v0
	v_mov_b32_e32 v128, v0
	v_mov_b32_e32 v129, v0
	v_mov_b32_e32 v130, v0
	v_mov_b32_e32 v131, v0
	v_mov_b32_e32 v132, v0
	v_mov_b32_e32 v133, v0
	v_mov_b32_e32 v134, v0
	v_mov_b32_e32 v135, v0
	v_mov_b32_e32 v72, v0
	v_mov_b32_e32 v73, v0
	v_mov_b32_e32 v74, v0
	v_mov_b32_e32 v75, v0
	v_mov_b32_e32 v76, v0
	v_mov_b32_e32 v77, v0
	v_mov_b32_e32 v78, v0
	v_mov_b32_e32 v79, v0
	v_mov_b32_e32 v104, v0
	v_mov_b32_e32 v105, v0
	v_mov_b32_e32 v106, v0
	v_mov_b32_e32 v107, v0
	v_mov_b32_e32 v108, v0
	v_mov_b32_e32 v109, v0
	v_mov_b32_e32 v110, v0
	v_mov_b32_e32 v111, v0
	v_mov_b32_e32 v120, v0
	v_mov_b32_e32 v121, v0
	v_mov_b32_e32 v122, v0
	v_mov_b32_e32 v123, v0
	v_mov_b32_e32 v124, v0
	v_mov_b32_e32 v125, v0
	v_mov_b32_e32 v126, v0
	v_mov_b32_e32 v127, v0
	v_mov_b32_e32 v136, v0
	v_mov_b32_e32 v137, v0
	v_mov_b32_e32 v138, v0
	v_mov_b32_e32 v139, v0
	v_mov_b32_e32 v140, v0
	v_mov_b32_e32 v141, v0
	v_mov_b32_e32 v142, v0
	v_mov_b32_e32 v143, v0
	s_add_i32 s1, s56, 0xffffff80
	s_and_b32 s0, s7, 0xf80
	s_and_b32 s1, s1, 0xf00
	s_add_u32 s57, s68, s1
	s_addc_u32 s70, s69, 0
	s_add_u32 s1, s66, s1
	s_addc_u32 s71, s67, 0
	s_and_b32 s72, s56, 0xf80
	s_add_u32 s80, s68, s72
	s_addc_u32 s73, s69, 0
	s_add_u32 s38, s66, s72
	s_addc_u32 s2, s67, 0
	s_cmp_eq_u32 s6, 28
	s_cselect_b32 s75, s46, s70
	s_cselect_b32 s74, s45, s57
	s_cselect_b32 s77, vcc_lo, s71
	s_cselect_b32 s76, s47, s1
	s_cselect_b32 s73, s97, s73
	s_cselect_b32 s72, s33, s80
	s_cselect_b32 s71, s5, s2
	s_cselect_b32 s70, vcc_hi, s38
	s_add_i32 s2, s84, 0x100
	s_add_u32 s0, s19, s0
	s_addc_u32 s1, s21, 0
; #define G_STAGE(bufoff, gbase, voff) do { _Pragma("unroll") for (int _i = 0; _i < 2; ++_i) \
;         __builtin_amdgcn_global_load_lds((const unsigned*)((const char*)(gbase) + (voff)[_i]), (LAS unsigned*)(lds + (bufoff) + ldsw + _i * 8192), 16, 0, 0); } while (0)
; #define G_LDA(dst, b, h) do { _Pragma("unroll") for (int m = 0; m < 4; ++m) _Pragma("unroll") for (int k = 0; k < 2; ++k) dst[m][k] = *(const LAS bf16x8*)(lds + G_SA(b, h) + aoff + m * 2048 + k * 1024); } while (0)
; #define G_LDB(dst, b, h) do { _Pragma("unroll") for (int n = 0; n < 2; ++n) _Pragma("unroll") for (int k = 0; k < 2; ++k) dst[n][k] = *(const LAS bf16x8*)(lds + G_SB(b, h) + boff + n * 2048 + k * 1024); } while (0)
; #define G_MMA(ai, bj, At, Bt) do { __builtin_amdgcn_s_setprio(1); _Pragma("unroll") for (int m = 0; m < 4; ++m) _Pragma("unroll") for (int n = 0; n < 2; ++n) _Pragma("unroll") for (int k = 0; k < 2; ++k) \
;         acc[ai][bj][m][n] = __builtin_amdgcn_mfma_f32_16x16x32_bf16(Bt[n][k], At[m][k], acc[ai][bj][m][n], 0, 0, 0); __builtin_amdgcn_s_setprio(0); } while (0)
; #define G_WAIT_V(n) asm volatile("s_waitcnt vmcnt(" #n ")" ::: "memory")
; #define G_WAIT_L(n) asm volatile("s_waitcnt lgkmcnt(" #n ")" ::: "memory")
; #define G_BAR __builtin_amdgcn_s_barrier()
; #define G_SCHED __builtin_amdgcn_sched_barrier(0)
; template <class J>
; DI void gemm_phase(LAS unsigned char* lds, const J& job) {
;     ...
;       G_LDB(B0, 0, 0); G_SCHED; G_LDA(At, 0, 0); G_STAGE(G_SA(1, 1), a1 + hstepA, voffA);
;       G_WAIT_L(8); G_BAR; G_WAIT_L(0); G_MMA(0, 0, At, B0); G_BAR; G_SCHED;
;       G_LDB(B1, 0, 1); G_STAGE(G_SB(0, 0), b2, voffB);
;       G_BAR; G_WAIT_L(0); G_MMA(0, 1, At, B1); G_BAR;
;       G_LDA(At, 0, 1); G_STAGE(G_SA(0, 0), a2, voffA);
;       G_BAR; G_WAIT_L(0); G_MMA(1, 0, At, B0); G_BAR; G_SCHED;
;       G_STAGE(G_SB(0, 1), b2 + hstepB, voffB);
;       G_WAIT_V(6); G_BAR; G_MMA(1, 1, At, B1); G_BAR;
.LBB0_74:
	ds_read_b128 v[84:87], v204
	ds_read_b128 v[88:91], v204 offset:1024
	ds_read_b128 v[96:99], v204 offset:2048
	ds_read_b128 v[100:103], v204 offset:3072
	s_add_i32 m0, s14, 0xc000
	ds_read_b128 v[154:157], v249
	ds_read_b128 v[158:161], v249 offset:1024
	ds_read_b128 v[162:165], v249 offset:2048
	ds_read_b128 v[166:169], v249 offset:3072
	ds_read_b128 v[170:173], v249 offset:4096
	ds_read_b128 v[174:177], v249 offset:5120
	ds_read_b128 v[178:181], v249 offset:6144
	ds_read_b128 v[182:185], v249 offset:7168
	global_load_lds_dwordx4 v148, s[0:1]
	s_add_i32 m0, s14, 0xe000
	s_nop 0
	global_load_lds_dwordx4 v150, s[0:1]
	s_waitcnt lgkmcnt(8)
	s_barrier
	s_waitcnt lgkmcnt(0)
	v_mfma_f32_16x16x32_bf16 v[140:143], v[84:87], v[154:157], v[140:143]
	v_mfma_f32_16x16x32_bf16 v[136:139], v[96:99], v[154:157], v[136:139]
	v_mfma_f32_16x16x32_bf16 v[124:127], v[84:87], v[162:165], v[124:127]
	v_mfma_f32_16x16x32_bf16 v[120:123], v[96:99], v[162:165], v[120:123]
	v_mfma_f32_16x16x32_bf16 v[108:111], v[84:87], v[170:173], v[108:111]
	v_mfma_f32_16x16x32_bf16 v[104:107], v[96:99], v[170:173], v[104:107]
	v_mfma_f32_16x16x32_bf16 v[76:79], v[84:87], v[178:181], v[76:79]
	v_mfma_f32_16x16x32_bf16 v[72:75], v[96:99], v[178:181], v[72:75]
	v_mfma_f32_16x16x32_bf16 v[140:143], v[88:91], v[158:161], v[140:143]
	v_mfma_f32_16x16x32_bf16 v[136:139], v[100:103], v[158:161], v[136:139]
	v_mfma_f32_16x16x32_bf16 v[124:127], v[88:91], v[166:169], v[124:127]
	v_mfma_f32_16x16x32_bf16 v[120:123], v[100:103], v[166:169], v[120:123]
	v_mfma_f32_16x16x32_bf16 v[108:111], v[88:91], v[174:177], v[108:111]
	v_mfma_f32_16x16x32_bf16 v[104:107], v[100:103], v[174:177], v[104:107]
	v_mfma_f32_16x16x32_bf16 v[76:79], v[88:91], v[182:185], v[76:79]
	v_mfma_f32_16x16x32_bf16 v[72:75], v[100:103], v[182:185], v[72:75]
	s_barrier
	s_add_i32 s38, s85, 0x100
	s_add_i32 s0, s2, s78
	s_mov_b32 m0, s0
	ds_read_b128 v[186:189], v204 offset:16384
	ds_read_b128 v[190:193], v204 offset:17408
	ds_read_b128 v[194:197], v204 offset:18432
	ds_read_b128 v[198:201], v204 offset:19456
	global_load_lds_dwordx4 v146, s[76:77]
	s_add_i32 m0, s0, 0x2000
	s_nop 0
	global_load_lds_dwordx4 v152, s[76:77]
	s_barrier
	s_waitcnt lgkmcnt(0)
	v_mfma_f32_16x16x32_bf16 v[132:135], v[186:189], v[154:157], v[132:135]
	v_mfma_f32_16x16x32_bf16 v[128:131], v[194:197], v[154:157], v[128:131]
	v_mfma_f32_16x16x32_bf16 v[116:119], v[186:189], v[162:165], v[116:119]
	v_mfma_f32_16x16x32_bf16 v[112:115], v[194:197], v[162:165], v[112:115]
	v_mfma_f32_16x16x32_bf16 v[92:95], v[186:189], v[170:173], v[92:95]
	v_mfma_f32_16x16x32_bf16 v[80:83], v[194:197], v[170:173], v[80:83]
	v_mfma_f32_16x16x32_bf16 v[68:71], v[186:189], v[178:181], v[68:71]
	v_mfma_f32_16x16x32_bf16 v[64:67], v[194:197], v[178:181], v[64:67]
	v_mfma_f32_16x16x32_bf16 v[132:135], v[190:193], v[158:161], v[132:135]
	v_mfma_f32_16x16x32_bf16 v[128:131], v[198:201], v[158:161], v[128:131]
	v_mfma_f32_16x16x32_bf16 v[116:119], v[190:193], v[166:169], v[116:119]
	v_mfma_f32_16x16x32_bf16 v[112:115], v[198:201], v[166:169], v[112:115]
	v_mfma_f32_16x16x32_bf16 v[92:95], v[190:193], v[174:177], v[92:95]
	v_mfma_f32_16x16x32_bf16 v[80:83], v[198:201], v[174:177], v[80:83]
	v_mfma_f32_16x16x32_bf16 v[68:71], v[190:193], v[182:185], v[68:71]
	v_mfma_f32_16x16x32_bf16 v[64:67], v[198:201], v[182:185], v[64:67]
	s_mov_b32 m0, s14
	s_barrier
	ds_read_b128 v[154:157], v249 offset:16384
	ds_read_b128 v[158:161], v249 offset:17408
	ds_read_b128 v[162:165], v249 offset:18432
	ds_read_b128 v[166:169], v249 offset:19456
	ds_read_b128 v[170:173], v249 offset:20480
	ds_read_b128 v[174:177], v249 offset:21504
	ds_read_b128 v[178:181], v249 offset:22528
	ds_read_b128 v[182:185], v249 offset:23552
	global_load_lds_dwordx4 v148, s[74:75]
	s_mov_b32 m0, s15
	s_nop 0
	global_load_lds_dwordx4 v150, s[74:75]
	s_barrier
	s_waitcnt lgkmcnt(0)
	v_mfma_f32_16x16x32_bf16 v[60:63], v[84:87], v[154:157], v[60:63]
	v_mfma_f32_16x16x32_bf16 v[56:59], v[96:99], v[154:157], v[56:59]
	v_mfma_f32_16x16x32_bf16 v[44:47], v[84:87], v[162:165], v[44:47]
	v_mfma_f32_16x16x32_bf16 v[40:43], v[96:99], v[162:165], v[40:43]
	v_mfma_f32_16x16x32_bf16 v[28:31], v[84:87], v[170:173], v[28:31]
	v_mfma_f32_16x16x32_bf16 v[24:27], v[96:99], v[170:173], v[24:27]
	v_mfma_f32_16x16x32_bf16 v[12:15], v[84:87], v[178:181], v[12:15]
	v_mfma_f32_16x16x32_bf16 v[8:11], v[96:99], v[178:181], v[8:11]
	v_mfma_f32_16x16x32_bf16 v[60:63], v[88:91], v[158:161], v[60:63]
	v_mfma_f32_16x16x32_bf16 v[56:59], v[100:103], v[158:161], v[56:59]
	v_mfma_f32_16x16x32_bf16 v[44:47], v[88:91], v[166:169], v[44:47]
	v_mfma_f32_16x16x32_bf16 v[40:43], v[100:103], v[166:169], v[40:43]
	v_mfma_f32_16x16x32_bf16 v[28:31], v[88:91], v[174:177], v[28:31]
	v_mfma_f32_16x16x32_bf16 v[24:27], v[100:103], v[174:177], v[24:27]
	v_mfma_f32_16x16x32_bf16 v[12:15], v[88:91], v[182:185], v[12:15]
	v_mfma_f32_16x16x32_bf16 v[8:11], v[100:103], v[182:185], v[8:11]
	s_barrier
	s_add_u32 s0, s76, 0x1000000
	s_addc_u32 s1, s77, 0
	s_add_i32 s2, s38, s78
	s_mov_b32 m0, s2
	s_nop 0
	global_load_lds_dwordx4 v146, s[0:1]
	s_add_i32 m0, s2, 0x2000
	s_nop 0
	global_load_lds_dwordx4 v152, s[0:1]
	s_waitcnt vmcnt(6)
	s_barrier
; #define G_STAGE(bufoff, gbase, voff) do { _Pragma("unroll") for (int _i = 0; _i < 2; ++_i) \
;         __builtin_amdgcn_global_load_lds((const unsigned*)((const char*)(gbase) + (voff)[_i]), (LAS unsigned*)(lds + (bufoff) + ldsw + _i * 8192), 16, 0, 0); } while (0)
; #define G_LDA(dst, b, h) do { _Pragma("unroll") for (int m = 0; m < 4; ++m) _Pragma("unroll") for (int k = 0; k < 2; ++k) dst[m][k] = *(const LAS bf16x8*)(lds + G_SA(b, h) + aoff + m * 2048 + k * 1024); } while (0)
; #define G_LDB(dst, b, h) do { _Pragma("unroll") for (int n = 0; n < 2; ++n) _Pragma("unroll") for (int k = 0; k < 2; ++k) dst[n][k] = *(const LAS bf16x8*)(lds + G_SB(b, h) + boff + n * 2048 + k * 1024); } while (0)
; #define G_MMA(ai, bj, At, Bt) do { __builtin_amdgcn_s_setprio(1); _Pragma("unroll") for (int m = 0; m < 4; ++m) _Pragma("unroll") for (int n = 0; n < 2; ++n) _Pragma("unroll") for (int k = 0; k < 2; ++k) \
;         acc[ai][bj][m][n] = __builtin_amdgcn_mfma_f32_16x16x32_bf16(Bt[n][k], At[m][k], acc[ai][bj][m][n], 0, 0, 0); __builtin_amdgcn_s_setprio(0); } while (0)
; #define G_WAIT_V(n) asm volatile("s_waitcnt vmcnt(" #n ")" ::: "memory")
; #define G_WAIT_L(n) asm volatile("s_waitcnt lgkmcnt(" #n ")" ::: "memory")
; #define G_BAR __builtin_amdgcn_s_barrier()
; #define G_SCHED __builtin_amdgcn_sched_barrier(0)
; template <class J>
; DI void gemm_phase(LAS unsigned char* lds, const J& job) {
;     ...
;       G_WAIT_V(6); G_BAR; G_MMA(1, 1, At, B1); G_BAR;
;       G_LDB(B0, 1, 0); G_SCHED; G_LDA(At, 1, 0); G_STAGE(G_SA(0, 1), a2 + hstepA, voffA);
;       G_WAIT_L(8); G_BAR; G_WAIT_L(0); G_MMA(0, 0, At, B0); G_BAR; G_SCHED;
;       G_LDB(B1, 1, 1); G_STAGE(G_SB(1, 0), b3, voffB);
;       G_BAR; G_WAIT_L(0); G_MMA(0, 1, At, B1); G_BAR;
;       G_LDA(At, 1, 1); G_STAGE(G_SA(1, 0), a3, voffA);
;       G_BAR; G_WAIT_L(0); G_MMA(1, 0, At, B0); G_BAR; G_SCHED;
	v_mfma_f32_16x16x32_bf16 v[52:55], v[186:189], v[154:157], v[52:55]
	v_mfma_f32_16x16x32_bf16 v[48:51], v[194:197], v[154:157], v[48:51]
	v_mfma_f32_16x16x32_bf16 v[36:39], v[186:189], v[162:165], v[36:39]
	v_mfma_f32_16x16x32_bf16 v[32:35], v[194:197], v[162:165], v[32:35]
	v_mfma_f32_16x16x32_bf16 v[20:23], v[186:189], v[170:173], v[20:23]
	v_mfma_f32_16x16x32_bf16 v[16:19], v[194:197], v[170:173], v[16:19]
	v_mfma_f32_16x16x32_bf16 v[4:7], v[186:189], v[178:181], v[4:7]
	v_mfma_f32_16x16x32_bf16 v[0:3], v[194:197], v[178:181], v[0:3]
	v_mfma_f32_16x16x32_bf16 v[52:55], v[190:193], v[158:161], v[52:55]
	v_mfma_f32_16x16x32_bf16 v[48:51], v[198:201], v[158:161], v[48:51]
	v_mfma_f32_16x16x32_bf16 v[36:39], v[190:193], v[166:169], v[36:39]
	v_mfma_f32_16x16x32_bf16 v[32:35], v[198:201], v[166:169], v[32:35]
	v_mfma_f32_16x16x32_bf16 v[20:23], v[190:193], v[174:177], v[20:23]
	v_mfma_f32_16x16x32_bf16 v[16:19], v[198:201], v[174:177], v[16:19]
	v_mfma_f32_16x16x32_bf16 v[4:7], v[190:193], v[182:185], v[4:7]
	v_mfma_f32_16x16x32_bf16 v[0:3], v[198:201], v[182:185], v[0:3]
	s_add_i32 s2, s88, 0x100
	s_barrier
	ds_read_b128 v[84:87], v204 offset:32768
	ds_read_b128 v[88:91], v204 offset:33792
	ds_read_b128 v[96:99], v204 offset:34816
	ds_read_b128 v[100:103], v204 offset:35840
	s_add_u32 s0, s74, 0x80000
	s_addc_u32 s1, s75, 0
	s_mov_b32 m0, s83
	ds_read_b128 v[154:157], v249 offset:32768
	ds_read_b128 v[158:161], v249 offset:33792
	ds_read_b128 v[162:165], v249 offset:34816
	ds_read_b128 v[166:169], v249 offset:35840
	ds_read_b128 v[170:173], v249 offset:36864
	ds_read_b128 v[174:177], v249 offset:37888
	ds_read_b128 v[178:181], v249 offset:38912
	ds_read_b128 v[182:185], v249 offset:39936
	global_load_lds_dwordx4 v148, s[0:1]
	s_mov_b32 m0, s36
	s_nop 0
	global_load_lds_dwordx4 v150, s[0:1]
	s_waitcnt lgkmcnt(8)
	s_barrier
	s_waitcnt lgkmcnt(0)
	v_mfma_f32_16x16x32_bf16 v[140:143], v[84:87], v[154:157], v[140:143]
	v_mfma_f32_16x16x32_bf16 v[136:139], v[96:99], v[154:157], v[136:139]
	v_mfma_f32_16x16x32_bf16 v[124:127], v[84:87], v[162:165], v[124:127]
	v_mfma_f32_16x16x32_bf16 v[120:123], v[96:99], v[162:165], v[120:123]
	v_mfma_f32_16x16x32_bf16 v[108:111], v[84:87], v[170:173], v[108:111]
	v_mfma_f32_16x16x32_bf16 v[104:107], v[96:99], v[170:173], v[104:107]
	v_mfma_f32_16x16x32_bf16 v[76:79], v[84:87], v[178:181], v[76:79]
	v_mfma_f32_16x16x32_bf16 v[72:75], v[96:99], v[178:181], v[72:75]
	v_mfma_f32_16x16x32_bf16 v[140:143], v[88:91], v[158:161], v[140:143]
	v_mfma_f32_16x16x32_bf16 v[136:139], v[100:103], v[158:161], v[136:139]
	v_mfma_f32_16x16x32_bf16 v[124:127], v[88:91], v[166:169], v[124:127]
	v_mfma_f32_16x16x32_bf16 v[120:123], v[100:103], v[166:169], v[120:123]
	v_mfma_f32_16x16x32_bf16 v[108:111], v[88:91], v[174:177], v[108:111]
	v_mfma_f32_16x16x32_bf16 v[104:107], v[100:103], v[174:177], v[104:107]
	v_mfma_f32_16x16x32_bf16 v[76:79], v[88:91], v[182:185], v[76:79]
	v_mfma_f32_16x16x32_bf16 v[72:75], v[100:103], v[182:185], v[72:75]
	s_barrier
	s_add_i32 s38, s89, 0x100
	s_add_i32 s0, s2, s78
	s_mov_b32 m0, s0
	ds_read_b128 v[186:189], v204 offset:49152
	ds_read_b128 v[190:193], v204 offset:50176
	ds_read_b128 v[194:197], v204 offset:51200
	ds_read_b128 v[198:201], v204 offset:52224
	global_load_lds_dwordx4 v146, s[70:71]
	s_add_i32 m0, s0, 0x2000
	s_nop 0
	global_load_lds_dwordx4 v152, s[70:71]
	s_barrier
	s_waitcnt lgkmcnt(0)
	v_mfma_f32_16x16x32_bf16 v[132:135], v[186:189], v[154:157], v[132:135]
	v_mfma_f32_16x16x32_bf16 v[128:131], v[194:197], v[154:157], v[128:131]
	v_mfma_f32_16x16x32_bf16 v[116:119], v[186:189], v[162:165], v[116:119]
	v_mfma_f32_16x16x32_bf16 v[112:115], v[194:197], v[162:165], v[112:115]
	v_mfma_f32_16x16x32_bf16 v[92:95], v[186:189], v[170:173], v[92:95]
	v_mfma_f32_16x16x32_bf16 v[80:83], v[194:197], v[170:173], v[80:83]
	v_mfma_f32_16x16x32_bf16 v[68:71], v[186:189], v[178:181], v[68:71]
	v_mfma_f32_16x16x32_bf16 v[64:67], v[194:197], v[178:181], v[64:67]
	v_mfma_f32_16x16x32_bf16 v[132:135], v[190:193], v[158:161], v[132:135]
	v_mfma_f32_16x16x32_bf16 v[128:131], v[198:201], v[158:161], v[128:131]
	v_mfma_f32_16x16x32_bf16 v[116:119], v[190:193], v[166:169], v[116:119]
	v_mfma_f32_16x16x32_bf16 v[112:115], v[198:201], v[166:169], v[112:115]
	v_mfma_f32_16x16x32_bf16 v[92:95], v[190:193], v[174:177], v[92:95]
	v_mfma_f32_16x16x32_bf16 v[80:83], v[198:201], v[174:177], v[80:83]
	v_mfma_f32_16x16x32_bf16 v[68:71], v[190:193], v[182:185], v[68:71]
	v_mfma_f32_16x16x32_bf16 v[64:67], v[198:201], v[182:185], v[64:67]
	s_mov_b32 m0, s24
	s_barrier
	ds_read_b128 v[154:157], v249 offset:49152
	ds_read_b128 v[158:161], v249 offset:50176
	ds_read_b128 v[162:165], v249 offset:51200
	ds_read_b128 v[166:169], v249 offset:52224
	ds_read_b128 v[170:173], v249 offset:53248
	ds_read_b128 v[174:177], v249 offset:54272
	ds_read_b128 v[178:181], v249 offset:55296
	ds_read_b128 v[182:185], v249 offset:56320
	global_load_lds_dwordx4 v148, s[72:73]
	s_mov_b32 m0, s25
	s_nop 0
	global_load_lds_dwordx4 v150, s[72:73]
	s_barrier
	s_waitcnt lgkmcnt(0)
	v_mfma_f32_16x16x32_bf16 v[60:63], v[84:87], v[154:157], v[60:63]
	v_mfma_f32_16x16x32_bf16 v[56:59], v[96:99], v[154:157], v[56:59]
	v_mfma_f32_16x16x32_bf16 v[44:47], v[84:87], v[162:165], v[44:47]
	v_mfma_f32_16x16x32_bf16 v[40:43], v[96:99], v[162:165], v[40:43]
	v_mfma_f32_16x16x32_bf16 v[28:31], v[84:87], v[170:173], v[28:31]
	v_mfma_f32_16x16x32_bf16 v[24:27], v[96:99], v[170:173], v[24:27]
	v_mfma_f32_16x16x32_bf16 v[12:15], v[84:87], v[178:181], v[12:15]
	v_mfma_f32_16x16x32_bf16 v[8:11], v[96:99], v[178:181], v[8:11]
	v_mfma_f32_16x16x32_bf16 v[60:63], v[88:91], v[158:161], v[60:63]
	v_mfma_f32_16x16x32_bf16 v[56:59], v[100:103], v[158:161], v[56:59]
	v_mfma_f32_16x16x32_bf16 v[44:47], v[88:91], v[166:169], v[44:47]
	v_mfma_f32_16x16x32_bf16 v[40:43], v[100:103], v[166:169], v[40:43]
	v_mfma_f32_16x16x32_bf16 v[28:31], v[88:91], v[174:177], v[28:31]
	v_mfma_f32_16x16x32_bf16 v[24:27], v[100:103], v[174:177], v[24:27]
	v_mfma_f32_16x16x32_bf16 v[12:15], v[88:91], v[182:185], v[12:15]
	v_mfma_f32_16x16x32_bf16 v[8:11], v[100:103], v[182:185], v[8:11]
	s_barrier
; #define G_STAGE(bufoff, gbase, voff) do { _Pragma("unroll") for (int _i = 0; _i < 2; ++_i) \
;         __builtin_amdgcn_global_load_lds((const unsigned*)((const char*)(gbase) + (voff)[_i]), (LAS unsigned*)(lds + (bufoff) + ldsw + _i * 8192), 16, 0, 0); } while (0)
; #define G_MMA(ai, bj, At, Bt) do { __builtin_amdgcn_s_setprio(1); _Pragma("unroll") for (int m = 0; m < 4; ++m) _Pragma("unroll") for (int n = 0; n < 2; ++n) _Pragma("unroll") for (int k = 0; k < 2; ++k) \
;         acc[ai][bj][m][n] = __builtin_amdgcn_mfma_f32_16x16x32_bf16(Bt[n][k], At[m][k], acc[ai][bj][m][n], 0, 0, 0); __builtin_amdgcn_s_setprio(0); } while (0)
; #define G_WAIT_V(n) asm volatile("s_waitcnt vmcnt(" #n ")" ::: "memory")
; #define G_BAR __builtin_amdgcn_s_barrier()
; template <class J>
; DI void gemm_phase(LAS unsigned char* lds, const J& job) {
;     ...
;     for (int t = 0; t < nt; t += 2) {
;       const bool last = (t == nt - 2);
;       const char* a1 = cA + G_KT(t + 1);
;       const char* a2 = last ? nA + G_KT(0) : cA + G_KT(t + 2); const char* b2 = last ? nB + G_KT(0) : cB + G_KT(t + 2);
;       const char* a3 = last ? nA + G_KT(1) : cA + G_KT(t + 3); const char* b3 = last ? nB + G_KT(1) : cB + G_KT(t + 3);
;     ...
;       G_STAGE(G_SB(1, 1), b3 + hstepB, voffB);
;       G_WAIT_V(6); G_BAR; G_MMA(1, 1, At, B1); G_BAR;
	s_add_u32 s0, s70, 0x1000000
	s_addc_u32 s1, s71, 0
	s_add_i32 s2, s38, s78
	s_mov_b32 m0, s2
	s_nop 0
	global_load_lds_dwordx4 v146, s[0:1]
	s_add_i32 m0, s2, 0x2000
	s_nop 0
	global_load_lds_dwordx4 v152, s[0:1]
	s_add_i32 s6, s6, 2
	s_addk_i32 s56, 0x100
	s_addk_i32 s7, 0x100
	s_add_i32 s1, s56, 0xffffff80
	s_and_b32 s0, s7, 0xf80
	s_and_b32 s1, s1, 0xf00
	s_add_u32 s57, s68, s1
	s_addc_u32 s70, s69, 0
	s_add_u32 s1, s66, s1
	s_addc_u32 s71, s67, 0
	s_and_b32 s72, s56, 0xf80
	s_add_u32 s80, s68, s72
	s_addc_u32 s73, s69, 0
	s_add_u32 s38, s66, s72
	s_addc_u32 s2, s67, 0
	s_cmp_eq_u32 s6, 28
	s_cselect_b32 s75, s46, s70
	s_cselect_b32 s74, s45, s57
	s_cselect_b32 s77, vcc_lo, s71
	s_cselect_b32 s76, s47, s1
	s_cselect_b32 s73, s97, s73
	s_cselect_b32 s72, s33, s80
	s_cselect_b32 s71, s5, s2
	s_cselect_b32 s70, vcc_hi, s38
	s_add_i32 s2, s84, 0x100
	s_add_u32 s0, s19, s0
	s_addc_u32 s1, s21, 0
	s_waitcnt vmcnt(6)
	s_barrier
	v_mfma_f32_16x16x32_bf16 v[52:55], v[186:189], v[154:157], v[52:55]
	v_mfma_f32_16x16x32_bf16 v[48:51], v[194:197], v[154:157], v[48:51]
	v_mfma_f32_16x16x32_bf16 v[36:39], v[186:189], v[162:165], v[36:39]
	v_mfma_f32_16x16x32_bf16 v[32:35], v[194:197], v[162:165], v[32:35]
	v_mfma_f32_16x16x32_bf16 v[20:23], v[186:189], v[170:173], v[20:23]
	v_mfma_f32_16x16x32_bf16 v[16:19], v[194:197], v[170:173], v[16:19]
	v_mfma_f32_16x16x32_bf16 v[4:7], v[186:189], v[178:181], v[4:7]
	v_mfma_f32_16x16x32_bf16 v[0:3], v[194:197], v[178:181], v[0:3]
	v_mfma_f32_16x16x32_bf16 v[52:55], v[190:193], v[158:161], v[52:55]
	v_mfma_f32_16x16x32_bf16 v[48:51], v[198:201], v[158:161], v[48:51]
	v_mfma_f32_16x16x32_bf16 v[36:39], v[190:193], v[166:169], v[36:39]
	v_mfma_f32_16x16x32_bf16 v[32:35], v[198:201], v[166:169], v[32:35]
	v_mfma_f32_16x16x32_bf16 v[20:23], v[190:193], v[174:177], v[20:23]
	v_mfma_f32_16x16x32_bf16 v[16:19], v[198:201], v[174:177], v[16:19]
	v_mfma_f32_16x16x32_bf16 v[4:7], v[190:193], v[182:185], v[4:7]
	v_mfma_f32_16x16x32_bf16 v[0:3], v[198:201], v[182:185], v[0:3]
	s_cmp_gt_u32 s6, 29
	s_barrier
	s_cbranch_scc0 .LBB0_74
;   DI void epi(const Acc& acc, const Unit& u, int wr, int wc, int fr, int fq) const {
;     const int cc = u.pn * 64 + 16 * wc + 4 * fq;
;     u32x2 zz[2][4][4];
; #pragma unroll
;     for (int ai = 0; ai < 2; ++ai)
; #pragma unroll
;       for (int m = 0; m < 4; ++m) {
;         const u16* zr = Z + (size_t)(u.pm * 256 + ai * HALF + wr * 64 + m * 16 + fr) * NGATE + cc;
; #pragma unroll
;         for (int br = 0; br < 4; ++br) zz[ai][m][br] = *(const u32x2*)(zr + br * 2048);
;       }
;     f32x4 bg[4];
; #pragma unroll
;     for (int br = 0; br < 4; ++br) bg[br] = *(const f32x4*)(bgate + br * 2048 + cc);
	v_mov_b32_e32 v84, v247
	v_mov_b32_e32 v85, v246
	s_lshl_b32 s0, s44, 6
	s_or_b32 s0, s0, s96
	v_lshl_add_u32 v84, v84, 2, s0
	s_lshl_b32 s0, s64, 8
	s_add_i32 s0, s0, s37
	v_add_u32_e32 v224, s0, v85
	v_ashrrev_i32_e32 v85, 31, v84
	v_lshlrev_b64 v[154:155], 1, v[84:85]
	v_ashrrev_i32_e32 v225, 31, v224
	v_lshl_add_u64 v[86:87], s[26:27], 0, v[154:155]
	v_lshlrev_b64 v[88:89], 14, v[224:225]
	v_lshl_add_u64 v[88:89], v[86:87], 0, v[88:89]
	v_add_co_u32_e32 v90, vcc, s82, v88
	v_add_u32_e32 v212, 16, v224
	s_nop 0
	v_addc_co_u32_e32 v91, vcc, 0, v89, vcc
	v_ashrrev_i32_e32 v213, 31, v212
	v_add_co_u32_e32 v96, vcc, s92, v88
	v_lshlrev_b64 v[98:99], 14, v[212:213]
	s_nop 0
	v_addc_co_u32_e32 v97, vcc, 0, v89, vcc
	v_lshl_add_u64 v[98:99], v[86:87], 0, v[98:99]
	v_add_co_u32_e32 v100, vcc, s82, v98
	v_add_u32_e32 v202, 32, v224
	s_nop 0
	v_addc_co_u32_e32 v101, vcc, 0, v99, vcc
	global_load_dwordx2 v[230:231], v[90:91], off offset:-4096
	global_load_dwordx2 v[226:227], v[90:91], off
	global_load_dwordx2 v[220:221], v[100:101], off offset:-4096
	global_load_dwordx2 v[214:215], v[100:101], off
	v_add_co_u32_e32 v90, vcc, s92, v98
	v_ashrrev_i32_e32 v203, 31, v202
	s_nop 0
	v_addc_co_u32_e32 v91, vcc, 0, v99, vcc
	global_load_dwordx2 v[232:233], v[88:89], off
	global_load_dwordx2 v[228:229], v[96:97], off
	global_load_dwordx2 v[222:223], v[98:99], off
	global_load_dwordx2 v[216:217], v[90:91], off
	v_lshlrev_b64 v[88:89], 14, v[202:203]
	v_lshl_add_u64 v[88:89], v[86:87], 0, v[88:89]
	v_add_co_u32_e32 v90, vcc, s82, v88
	v_add_u32_e32 v190, 48, v224
	s_nop 0
	v_addc_co_u32_e32 v91, vcc, 0, v89, vcc
	v_ashrrev_i32_e32 v191, 31, v190
	v_add_co_u32_e32 v96, vcc, s92, v88
	v_lshlrev_b64 v[98:99], 14, v[190:191]
	s_nop 0
	v_addc_co_u32_e32 v97, vcc, 0, v89, vcc
	v_lshl_add_u64 v[98:99], v[86:87], 0, v[98:99]
	v_add_co_u32_e32 v100, vcc, s82, v98
	v_add_u32_e32 v184, 0x80, v224
	s_nop 0
	v_addc_co_u32_e32 v101, vcc, 0, v99, vcc
	global_load_dwordx2 v[210:211], v[90:91], off offset:-4096
	global_load_dwordx2 v[206:207], v[90:91], off
	global_load_dwordx2 v[200:201], v[100:101], off offset:-4096
	global_load_dwordx2 v[192:193], v[100:101], off
	v_add_co_u32_e32 v90, vcc, s92, v98
	v_lshl_add_u64 v[84:85], v[84:85], 2, s[12:13]
	v_ashrrev_i32_e32 v185, 31, v184
	v_addc_co_u32_e32 v91, vcc, 0, v99, vcc
	global_load_dwordx4 v[100:103], v[84:85], off
	global_load_dwordx2 v[218:219], v[88:89], off
	global_load_dwordx2 v[208:209], v[96:97], off
	global_load_dwordx2 v[204:205], v[98:99], off
	global_load_dwordx2 v[198:199], v[90:91], off
	v_lshlrev_b64 v[88:89], 14, v[184:185]
	v_lshl_add_u64 v[88:89], v[86:87], 0, v[88:89]
	v_add_co_u32_e32 v90, vcc, s82, v88
	v_add_u32_e32 v174, 0x90, v224
	s_nop 0
	v_addc_co_u32_e32 v91, vcc, 0, v89, vcc
	v_add_co_u32_e32 v156, vcc, s92, v88
	v_ashrrev_i32_e32 v175, 31, v174
	s_nop 0
	v_addc_co_u32_e32 v157, vcc, 0, v89, vcc
	v_add_co_u32_e32 v96, vcc, s82, v84
	v_lshlrev_b64 v[158:159], 14, v[174:175]
	s_nop 0
	v_addc_co_u32_e32 v97, vcc, 0, v85, vcc
	global_load_dwordx4 v[96:99], v[96:97], off
	v_lshl_add_u64 v[158:159], v[86:87], 0, v[158:159]
	v_add_co_u32_e32 v160, vcc, s82, v158
	v_add_u32_e32 v164, 0xa0, v224
	s_nop 0
	v_addc_co_u32_e32 v161, vcc, 0, v159, vcc
	global_load_dwordx2 v[194:195], v[90:91], off offset:-4096
	global_load_dwordx2 v[186:187], v[90:91], off
	global_load_dwordx2 v[180:181], v[160:161], off offset:-4096
	global_load_dwordx2 v[176:177], v[160:161], off
	v_add_co_u32_e32 v90, vcc, s92, v158
	v_ashrrev_i32_e32 v165, 31, v164
	s_nop 0
	v_addc_co_u32_e32 v91, vcc, 0, v159, vcc
	global_load_dwordx2 v[196:197], v[88:89], off
	global_load_dwordx2 v[188:189], v[156:157], off
	global_load_dwordx2 v[182:183], v[158:159], off
	global_load_dwordx2 v[178:179], v[90:91], off
	v_lshlrev_b64 v[88:89], 14, v[164:165]
	v_lshl_add_u64 v[162:163], v[86:87], 0, v[88:89]
	v_add_co_u32_e32 v158, vcc, s82, v162
	v_add_u32_e32 v156, 0xb0, v224
	s_nop 0
	v_addc_co_u32_e32 v159, vcc, 0, v163, vcc
	v_add_co_u32_e32 v168, vcc, s92, v162
	v_ashrrev_i32_e32 v157, 31, v156
	s_nop 0
	v_addc_co_u32_e32 v169, vcc, 0, v163, vcc
	v_add_co_u32_e32 v88, vcc, s54, v84
	v_lshlrev_b64 v[160:161], 14, v[156:157]
	s_nop 0
	v_addc_co_u32_e32 v89, vcc, 0, v85, vcc
	global_load_dwordx4 v[88:91], v[88:89], off
	v_lshl_add_u64 v[250:251], v[86:87], 0, v[160:161]
	v_add_co_u32_e32 v86, vcc, s82, v250
	s_mov_b32 s44, s20
	s_nop 0
	v_addc_co_u32_e32 v87, vcc, 0, v251, vcc
	v_add_co_u32_e32 v84, vcc, s55, v84
	global_load_dwordx2 v[170:171], v[158:159], off offset:-4096
	global_load_dwordx2 v[166:167], v[158:159], off
	global_load_dwordx2 v[160:161], v[86:87], off offset:-4096
	s_nop 0
	global_load_dwordx2 v[158:159], v[86:87], off
	v_addc_co_u32_e32 v85, vcc, 0, v85, vcc
	global_load_dwordx4 v[84:87], v[84:85], off
	v_add_co_u32_e32 v252, vcc, s92, v250
	s_mov_b32 s64, s18
	s_nop 0
	v_addc_co_u32_e32 v253, vcc, 0, v251, vcc
	s_and_b64 vcc, exec, s[8:9]
	s_mov_b64 s[66:67], s[62:63]
	s_mov_b64 s[68:69], s[22:23]
	v_readlane_b32 s0, v255, 23
	s_cmpk_gt_u32 s0, 0xff
	s_cbranch_scc1 .Lds_gate_x
	s_barrier

;   DI const char* aptr(const Unit& u) const { return (const char*)(h + (size_t)u.pm * 256 * DM); }
;   DI const char* bptr(const Unit& u) const { return (const char*)(winT + (size_t)u.pn * 256 * DM); }
;   DI bool next(int i, Unit& u) const { const int L = i * G + c; if (L >= nunits) return false; u.kind = 0; decode_unit(L, 65, 32, u.pm, u.pn); return true; }
;   DI const char* aptr(const Unit& u) const { return (const char*)(y + (size_t)u.pm * 256 * DM + (u.pn >> 3) * 512); }
;   DI const char* bptr(const Unit& u) const { return (const char*)(wbT + (size_t)u.pn * 256 * 512); }
;   DI const char* aptr(const Unit& u) const { return (const char*)(h + (size_t)u.pm * 256 * DM); }
;   DI const char* bptr(const Unit& u) const { return (const char*)(wgT + (size_t)u.pn * 64 * DM); }
;   DI const char* aptr(const Unit& u) const { return (const char*)(mixed + (size_t)u.pm * 256 * DM); }
;   DI const char* bptr(const Unit& u) const { return (const char*)(woutT + (size_t)u.pn * 256 * DM); }
; template <class J>
; DI void gemm_phase(LAS unsigned char* lds, const J& job) {
;     ...
;     const bool has_next = job.next(ui + 1, nxt);
;     const char* nA = has_next ? job.aptr(nxt) : cA; const char* nB = has_next ? job.bptr(nxt) : cB;
;     for (int t = 0; t < nt; t += 2) {
;       const bool last = (t == nt - 2);
;       const char* a1 = cA + G_KT(t + 1);
;       const char* a2 = last ? nA + G_KT(0) : cA + G_KT(t + 2); const char* b2 = last ? nB + G_KT(0) : cB + G_KT(t + 2);
;       const char* a3 = last ? nA + G_KT(1) : cA + G_KT(t + 3); const char* b3 = last ? nB + G_KT(1) : cB + G_KT(t + 3);
;     ...
; #pragma unroll
;     for (int a = 0; a < 2; ++a)
; #pragma unroll
;       for (int b = 0; b < 2; ++b)
; #pragma unroll
;         for (int m = 0; m < 4; ++m)
; #pragma unroll
;           for (int n = 0; n < 2; ++n) acc[a][b][m][n] = (f32x4){0.f, 0.f, 0.f, 0.f};
;     cur = nxt; cA = nA; cB = nB; ++ui;
.LBB0_103:
	s_lshl_b32 s0, s8, 6
	s_ashr_i32 s17, s16, 31
	s_and_b32 s18, s0, 0xfffffe00
	s_lshl_b64 s[6:7], s[16:17], 20
	s_ashr_i32 s19, s18, 31
	s_add_u32 s0, s10, s6
	s_addc_u32 s1, s11, s7
	s_lshl_b64 s[6:7], s[18:19], 1
	s_add_u32 s18, s0, s6
	s_addc_u32 s19, s1, s7
	s_ashr_i32 s9, s8, 31
	s_lshl_b64 s[6:7], s[8:9], 18
	s_add_u32 s20, s14, s6
	s_addc_u32 s21, s15, s7
	s_add_u32 s9, s64, 0x80000
	s_addc_u32 s17, s65, 0
	s_and_b64 s[6:7], s[66:67], exec
	s_cselect_b32 s6, s18, s64
	s_cselect_b32 s0, s21, s63
	s_cselect_b32 s1, s20, s62
	s_cselect_b32 s5, s19, s65
	s_add_u32 s47, s6, s23
	s_addc_u32 s83, s5, 0
	s_add_u32 s86, s1, s23
	s_addc_u32 s87, s0, 0
	s_add_u32 s33, s6, s74
	s_addc_u32 s94, s5, 0
	s_add_u32 s96, s1, s74
	v_mov_b32_e32 v0, 0
	s_addc_u32 s5, s0, 0
	s_mov_b32 s6, -2
	s_mov_b32 s7, s78
	s_mov_b32 s56, s77
	v_mov_b32_e32 v1, v0
	v_mov_b32_e32 v2, v0
	v_mov_b32_e32 v3, v0
	v_mov_b32_e32 v4, v0
	v_mov_b32_e32 v5, v0
	v_mov_b32_e32 v6, v0
	v_mov_b32_e32 v7, v0
	v_mov_b32_e32 v8, v0
	v_mov_b32_e32 v9, v0
	v_mov_b32_e32 v10, v0
	v_mov_b32_e32 v11, v0
	v_mov_b32_e32 v16, v0
	v_mov_b32_e32 v17, v0
	v_mov_b32_e32 v18, v0
	v_mov_b32_e32 v19, v0
	v_mov_b32_e32 v24, v0
	v_mov_b32_e32 v25, v0
	v_mov_b32_e32 v26, v0
	v_mov_b32_e32 v27, v0
	v_mov_b32_e32 v32, v0
	v_mov_b32_e32 v33, v0
	v_mov_b32_e32 v34, v0
	v_mov_b32_e32 v35, v0
	v_mov_b32_e32 v40, v0
	v_mov_b32_e32 v41, v0
	v_mov_b32_e32 v42, v0
	v_mov_b32_e32 v43, v0
	v_mov_b32_e32 v48, v0
	v_mov_b32_e32 v49, v0
	v_mov_b32_e32 v50, v0
	v_mov_b32_e32 v51, v0
	v_mov_b32_e32 v12, v0
	v_mov_b32_e32 v13, v0
	v_mov_b32_e32 v14, v0
	v_mov_b32_e32 v15, v0
	v_mov_b32_e32 v20, v0
	v_mov_b32_e32 v21, v0
	v_mov_b32_e32 v22, v0
	v_mov_b32_e32 v23, v0
	v_mov_b32_e32 v28, v0
	v_mov_b32_e32 v29, v0
	v_mov_b32_e32 v30, v0
	v_mov_b32_e32 v31, v0
	v_mov_b32_e32 v36, v0
	v_mov_b32_e32 v37, v0
	v_mov_b32_e32 v38, v0
	v_mov_b32_e32 v39, v0
	v_mov_b32_e32 v44, v0
	v_mov_b32_e32 v45, v0
	v_mov_b32_e32 v46, v0
	v_mov_b32_e32 v47, v0
	v_mov_b32_e32 v52, v0
	v_mov_b32_e32 v53, v0
	v_mov_b32_e32 v54, v0
	v_mov_b32_e32 v55, v0
	v_mov_b32_e32 v56, v0
	v_mov_b32_e32 v57, v0
	v_mov_b32_e32 v58, v0
	v_mov_b32_e32 v59, v0
	v_mov_b32_e32 v60, v0
	v_mov_b32_e32 v61, v0
	v_mov_b32_e32 v62, v0
	v_mov_b32_e32 v63, v0
	v_mov_b32_e32 v64, v0
	v_mov_b32_e32 v65, v0
	v_mov_b32_e32 v66, v0
	v_mov_b32_e32 v67, v0
	v_mov_b32_e32 v68, v0
	v_mov_b32_e32 v69, v0
	v_mov_b32_e32 v70, v0
	v_mov_b32_e32 v71, v0
	v_mov_b32_e32 v72, v0
	v_mov_b32_e32 v73, v0
	v_mov_b32_e32 v74, v0
	v_mov_b32_e32 v75, v0
	v_mov_b32_e32 v80, v0
	v_mov_b32_e32 v81, v0
	v_mov_b32_e32 v82, v0
	v_mov_b32_e32 v83, v0
	v_mov_b32_e32 v88, v0
	v_mov_b32_e32 v89, v0
	v_mov_b32_e32 v90, v0
	v_mov_b32_e32 v91, v0
	v_mov_b32_e32 v96, v0
	v_mov_b32_e32 v97, v0
	v_mov_b32_e32 v98, v0
	v_mov_b32_e32 v99, v0
	v_mov_b32_e32 v104, v0
	v_mov_b32_e32 v105, v0
	v_mov_b32_e32 v106, v0
	v_mov_b32_e32 v107, v0
	v_mov_b32_e32 v112, v0
	v_mov_b32_e32 v113, v0
	v_mov_b32_e32 v114, v0
	v_mov_b32_e32 v115, v0
	v_mov_b32_e32 v76, v0
	v_mov_b32_e32 v77, v0
	v_mov_b32_e32 v78, v0
	v_mov_b32_e32 v79, v0
	v_mov_b32_e32 v84, v0
	v_mov_b32_e32 v85, v0
	v_mov_b32_e32 v86, v0
	v_mov_b32_e32 v87, v0
	v_mov_b32_e32 v92, v0
	v_mov_b32_e32 v93, v0
	v_mov_b32_e32 v94, v0
	v_mov_b32_e32 v95, v0
	v_mov_b32_e32 v100, v0
	v_mov_b32_e32 v101, v0
	v_mov_b32_e32 v102, v0
	v_mov_b32_e32 v103, v0
	v_mov_b32_e32 v108, v0
	v_mov_b32_e32 v109, v0
	v_mov_b32_e32 v110, v0
	v_mov_b32_e32 v111, v0
	v_mov_b32_e32 v116, v0
	v_mov_b32_e32 v117, v0
	v_mov_b32_e32 v118, v0
	v_mov_b32_e32 v119, v0
	v_mov_b32_e32 v120, v0
	v_mov_b32_e32 v121, v0
	v_mov_b32_e32 v122, v0
	v_mov_b32_e32 v123, v0
	v_mov_b32_e32 v124, v0
	v_mov_b32_e32 v125, v0
	v_mov_b32_e32 v126, v0
	v_mov_b32_e32 v127, v0
	s_add_i32 s1, s56, 0xffffff80
	s_and_b32 s0, s7, 0x380
	s_and_b32 s1, s1, 0x380
	s_add_u32 s57, s64, s1
	s_addc_u32 s66, s65, 0
	s_add_u32 s1, s62, s1
	s_addc_u32 s67, s63, 0
	s_and_b32 s68, s56, 0x380
	s_add_u32 s80, s64, s68
	s_addc_u32 s69, s65, 0
	s_add_u32 s97, s62, s68
	s_addc_u32 vcc_lo, s63, 0
	s_cmp_eq_u32 s6, 4
	s_cselect_b32 s71, s83, s66
	s_cselect_b32 s70, s47, s57
	s_cselect_b32 s73, s87, s67
	s_cselect_b32 s72, s86, s1
	s_cselect_b32 s69, s94, s69
	s_cselect_b32 s68, s33, s80
	s_cselect_b32 s67, s5, vcc_lo
	s_cselect_b32 s66, s96, s97
	s_add_i32 s1, s84, 0x100
	s_add_u32 vcc_lo, s9, s0
	s_addc_u32 vcc_hi, s17, 0
; #define G_STAGE(bufoff, gbase, voff) do { _Pragma("unroll") for (int _i = 0; _i < 2; ++_i) \
;         __builtin_amdgcn_global_load_lds((const unsigned*)((const char*)(gbase) + (voff)[_i]), (LAS unsigned*)(lds + (bufoff) + ldsw + _i * 8192), 16, 0, 0); } while (0)
; #define G_LDA(dst, b, h) do { _Pragma("unroll") for (int m = 0; m < 4; ++m) _Pragma("unroll") for (int k = 0; k < 2; ++k) dst[m][k] = *(const LAS bf16x8*)(lds + G_SA(b, h) + aoff + m * 2048 + k * 1024); } while (0)
; #define G_LDB(dst, b, h) do { _Pragma("unroll") for (int n = 0; n < 2; ++n) _Pragma("unroll") for (int k = 0; k < 2; ++k) dst[n][k] = *(const LAS bf16x8*)(lds + G_SB(b, h) + boff + n * 2048 + k * 1024); } while (0)
; #define G_MMA(ai, bj, At, Bt) do { __builtin_amdgcn_s_setprio(1); _Pragma("unroll") for (int m = 0; m < 4; ++m) _Pragma("unroll") for (int n = 0; n < 2; ++n) _Pragma("unroll") for (int k = 0; k < 2; ++k) \
;         acc[ai][bj][m][n] = __builtin_amdgcn_mfma_f32_16x16x32_bf16(Bt[n][k], At[m][k], acc[ai][bj][m][n], 0, 0, 0); __builtin_amdgcn_s_setprio(0); } while (0)
; #define G_WAIT_V(n) asm volatile("s_waitcnt vmcnt(" #n ")" ::: "memory")
; #define G_WAIT_L(n) asm volatile("s_waitcnt lgkmcnt(" #n ")" ::: "memory")
; #define G_BAR __builtin_amdgcn_s_barrier()
; #define G_SCHED __builtin_amdgcn_sched_barrier(0)
; template <class J>
; DI void gemm_phase(LAS unsigned char* lds, const J& job) {
;     ...
;       G_LDB(B0, 0, 0); G_SCHED; G_LDA(At, 0, 0); G_STAGE(G_SA(1, 1), a1 + hstepA, voffA);
;       G_WAIT_L(8); G_BAR; G_WAIT_L(0); G_MMA(0, 0, At, B0); G_BAR; G_SCHED;
;       G_LDB(B1, 0, 1); G_STAGE(G_SB(0, 0), b2, voffB);
;       G_BAR; G_WAIT_L(0); G_MMA(0, 1, At, B1); G_BAR;
;       G_LDA(At, 0, 1); G_STAGE(G_SA(0, 0), a2, voffA);
;       G_BAR; G_WAIT_L(0); G_MMA(1, 0, At, B0); G_BAR; G_SCHED;
;       G_STAGE(G_SB(0, 1), b2 + hstepB, voffB);
;       G_WAIT_V(6); G_BAR; G_MMA(1, 1, At, B1); G_BAR;
.LBB0_104:
	ds_read_b128 v[140:143], v208
	ds_read_b128 v[148:151], v208 offset:1024
	ds_read_b128 v[152:155], v208 offset:2048
	ds_read_b128 v[156:159], v208 offset:3072
	s_add_i32 m0, s25, 0xc000
	ds_read_b128 v[160:163], v139
	ds_read_b128 v[164:167], v139 offset:1024
	ds_read_b128 v[168:171], v139 offset:2048
	ds_read_b128 v[172:175], v139 offset:3072
	ds_read_b128 v[176:179], v139 offset:4096
	ds_read_b128 v[180:183], v139 offset:5120
	ds_read_b128 v[184:187], v139 offset:6144
	ds_read_b128 v[188:191], v139 offset:7168
	global_load_lds_dwordx4 v132, vcc
	s_add_i32 m0, s25, 0xe000
	s_nop 0
	global_load_lds_dwordx4 v130, vcc
	s_waitcnt lgkmcnt(8)
	s_barrier
	s_waitcnt lgkmcnt(0)
	v_mfma_f32_16x16x32_bf16 v[124:127], v[140:143], v[160:163], v[124:127]
	v_mfma_f32_16x16x32_bf16 v[120:123], v[152:155], v[160:163], v[120:123]
	v_mfma_f32_16x16x32_bf16 v[116:119], v[140:143], v[168:171], v[116:119]
	v_mfma_f32_16x16x32_bf16 v[108:111], v[152:155], v[168:171], v[108:111]
	v_mfma_f32_16x16x32_bf16 v[100:103], v[140:143], v[176:179], v[100:103]
	v_mfma_f32_16x16x32_bf16 v[92:95], v[152:155], v[176:179], v[92:95]
	v_mfma_f32_16x16x32_bf16 v[84:87], v[140:143], v[184:187], v[84:87]
	v_mfma_f32_16x16x32_bf16 v[76:79], v[152:155], v[184:187], v[76:79]
	v_mfma_f32_16x16x32_bf16 v[124:127], v[148:151], v[164:167], v[124:127]
	v_mfma_f32_16x16x32_bf16 v[120:123], v[156:159], v[164:167], v[120:123]
	v_mfma_f32_16x16x32_bf16 v[116:119], v[148:151], v[172:175], v[116:119]
	v_mfma_f32_16x16x32_bf16 v[108:111], v[156:159], v[172:175], v[108:111]
	v_mfma_f32_16x16x32_bf16 v[100:103], v[148:151], v[180:183], v[100:103]
	v_mfma_f32_16x16x32_bf16 v[92:95], v[156:159], v[180:183], v[92:95]
	v_mfma_f32_16x16x32_bf16 v[84:87], v[148:151], v[188:191], v[84:87]
	v_mfma_f32_16x16x32_bf16 v[76:79], v[156:159], v[188:191], v[76:79]
	s_barrier
	s_add_i32 s0, s85, 0x100
	s_add_i32 s1, s1, s24
	ds_read_b128 v[192:195], v208 offset:16384
	ds_read_b128 v[196:199], v208 offset:17408
	ds_read_b128 v[200:203], v208 offset:18432
	ds_read_b128 v[204:207], v208 offset:19456
	s_mov_b32 m0, s1
	s_nop 0
	global_load_lds_dwordx4 v146, s[72:73]
	s_add_i32 m0, s1, 0x2000
	s_nop 0
	global_load_lds_dwordx4 v128, s[72:73]
	s_barrier
	s_waitcnt lgkmcnt(0)
	v_mfma_f32_16x16x32_bf16 v[112:115], v[192:195], v[160:163], v[112:115]
	v_mfma_f32_16x16x32_bf16 v[104:107], v[200:203], v[160:163], v[104:107]
	v_mfma_f32_16x16x32_bf16 v[96:99], v[192:195], v[168:171], v[96:99]
	v_mfma_f32_16x16x32_bf16 v[88:91], v[200:203], v[168:171], v[88:91]
	v_mfma_f32_16x16x32_bf16 v[80:83], v[192:195], v[176:179], v[80:83]
	v_mfma_f32_16x16x32_bf16 v[72:75], v[200:203], v[176:179], v[72:75]
	v_mfma_f32_16x16x32_bf16 v[68:71], v[192:195], v[184:187], v[68:71]
	v_mfma_f32_16x16x32_bf16 v[64:67], v[200:203], v[184:187], v[64:67]
	v_mfma_f32_16x16x32_bf16 v[112:115], v[196:199], v[164:167], v[112:115]
	v_mfma_f32_16x16x32_bf16 v[104:107], v[204:207], v[164:167], v[104:107]
	v_mfma_f32_16x16x32_bf16 v[96:99], v[196:199], v[172:175], v[96:99]
	v_mfma_f32_16x16x32_bf16 v[88:91], v[204:207], v[172:175], v[88:91]
	v_mfma_f32_16x16x32_bf16 v[80:83], v[196:199], v[180:183], v[80:83]
	v_mfma_f32_16x16x32_bf16 v[72:75], v[204:207], v[180:183], v[72:75]
	v_mfma_f32_16x16x32_bf16 v[68:71], v[196:199], v[188:191], v[68:71]
	v_mfma_f32_16x16x32_bf16 v[64:67], v[204:207], v[188:191], v[64:67]
	s_mov_b32 m0, s25
	s_barrier
	ds_read_b128 v[160:163], v139 offset:16384
	ds_read_b128 v[164:167], v139 offset:17408
	ds_read_b128 v[168:171], v139 offset:18432
	ds_read_b128 v[172:175], v139 offset:19456
	ds_read_b128 v[176:179], v139 offset:20480
	ds_read_b128 v[180:183], v139 offset:21504
	ds_read_b128 v[184:187], v139 offset:22528
	ds_read_b128 v[188:191], v139 offset:23552
	global_load_lds_dwordx4 v132, s[70:71]
	s_mov_b32 m0, s36
	s_nop 0
	global_load_lds_dwordx4 v130, s[70:71]
	s_barrier
	s_waitcnt lgkmcnt(0)
	v_mfma_f32_16x16x32_bf16 v[60:63], v[140:143], v[160:163], v[60:63]
	v_mfma_f32_16x16x32_bf16 v[56:59], v[152:155], v[160:163], v[56:59]
	v_mfma_f32_16x16x32_bf16 v[52:55], v[140:143], v[168:171], v[52:55]
	v_mfma_f32_16x16x32_bf16 v[44:47], v[152:155], v[168:171], v[44:47]
	v_mfma_f32_16x16x32_bf16 v[36:39], v[140:143], v[176:179], v[36:39]
	v_mfma_f32_16x16x32_bf16 v[28:31], v[152:155], v[176:179], v[28:31]
	v_mfma_f32_16x16x32_bf16 v[20:23], v[140:143], v[184:187], v[20:23]
	v_mfma_f32_16x16x32_bf16 v[12:15], v[152:155], v[184:187], v[12:15]
	v_mfma_f32_16x16x32_bf16 v[60:63], v[148:151], v[164:167], v[60:63]
	v_mfma_f32_16x16x32_bf16 v[56:59], v[156:159], v[164:167], v[56:59]
	v_mfma_f32_16x16x32_bf16 v[52:55], v[148:151], v[172:175], v[52:55]
	v_mfma_f32_16x16x32_bf16 v[44:47], v[156:159], v[172:175], v[44:47]
	v_mfma_f32_16x16x32_bf16 v[36:39], v[148:151], v[180:183], v[36:39]
	v_mfma_f32_16x16x32_bf16 v[28:31], v[156:159], v[180:183], v[28:31]
	v_mfma_f32_16x16x32_bf16 v[20:23], v[148:151], v[188:191], v[20:23]
	v_mfma_f32_16x16x32_bf16 v[12:15], v[156:159], v[188:191], v[12:15]
	s_barrier
	s_add_u32 s72, s72, 0x20000
	s_addc_u32 s73, s73, 0
	s_add_i32 s0, s0, s24
	s_mov_b32 m0, s0
	s_nop 0
	global_load_lds_dwordx4 v146, s[72:73]
	s_add_i32 m0, s0, 0x2000
	s_nop 0
	global_load_lds_dwordx4 v128, s[72:73]
	s_waitcnt vmcnt(6)
	s_barrier
; #define G_STAGE(bufoff, gbase, voff) do { _Pragma("unroll") for (int _i = 0; _i < 2; ++_i) \
;         __builtin_amdgcn_global_load_lds((const unsigned*)((const char*)(gbase) + (voff)[_i]), (LAS unsigned*)(lds + (bufoff) + ldsw + _i * 8192), 16, 0, 0); } while (0)
; #define G_LDA(dst, b, h) do { _Pragma("unroll") for (int m = 0; m < 4; ++m) _Pragma("unroll") for (int k = 0; k < 2; ++k) dst[m][k] = *(const LAS bf16x8*)(lds + G_SA(b, h) + aoff + m * 2048 + k * 1024); } while (0)
; #define G_LDB(dst, b, h) do { _Pragma("unroll") for (int n = 0; n < 2; ++n) _Pragma("unroll") for (int k = 0; k < 2; ++k) dst[n][k] = *(const LAS bf16x8*)(lds + G_SB(b, h) + boff + n * 2048 + k * 1024); } while (0)
; #define G_MMA(ai, bj, At, Bt) do { __builtin_amdgcn_s_setprio(1); _Pragma("unroll") for (int m = 0; m < 4; ++m) _Pragma("unroll") for (int n = 0; n < 2; ++n) _Pragma("unroll") for (int k = 0; k < 2; ++k) \
;         acc[ai][bj][m][n] = __builtin_amdgcn_mfma_f32_16x16x32_bf16(Bt[n][k], At[m][k], acc[ai][bj][m][n], 0, 0, 0); __builtin_amdgcn_s_setprio(0); } while (0)
; #define G_WAIT_V(n) asm volatile("s_waitcnt vmcnt(" #n ")" ::: "memory")
; #define G_WAIT_L(n) asm volatile("s_waitcnt lgkmcnt(" #n ")" ::: "memory")
; #define G_BAR __builtin_amdgcn_s_barrier()
; #define G_SCHED __builtin_amdgcn_sched_barrier(0)
; template <class J>
; DI void gemm_phase(LAS unsigned char* lds, const J& job) {
;     ...
;       G_WAIT_V(6); G_BAR; G_MMA(1, 1, At, B1); G_BAR;
;       G_LDB(B0, 1, 0); G_SCHED; G_LDA(At, 1, 0); G_STAGE(G_SA(0, 1), a2 + hstepA, voffA);
;       G_WAIT_L(8); G_BAR; G_WAIT_L(0); G_MMA(0, 0, At, B0); G_BAR; G_SCHED;
;       G_LDB(B1, 1, 1); G_STAGE(G_SB(1, 0), b3, voffB);
;       G_BAR; G_WAIT_L(0); G_MMA(0, 1, At, B1); G_BAR;
;       G_LDA(At, 1, 1); G_STAGE(G_SA(1, 0), a3, voffA);
;       G_BAR; G_WAIT_L(0); G_MMA(1, 0, At, B0); G_BAR; G_SCHED;
	v_mfma_f32_16x16x32_bf16 v[48:51], v[192:195], v[160:163], v[48:51]
	v_mfma_f32_16x16x32_bf16 v[40:43], v[200:203], v[160:163], v[40:43]
	v_mfma_f32_16x16x32_bf16 v[32:35], v[192:195], v[168:171], v[32:35]
	v_mfma_f32_16x16x32_bf16 v[24:27], v[200:203], v[168:171], v[24:27]
	v_mfma_f32_16x16x32_bf16 v[16:19], v[192:195], v[176:179], v[16:19]
	v_mfma_f32_16x16x32_bf16 v[8:11], v[200:203], v[176:179], v[8:11]
	v_mfma_f32_16x16x32_bf16 v[4:7], v[192:195], v[184:187], v[4:7]
	v_mfma_f32_16x16x32_bf16 v[0:3], v[200:203], v[184:187], v[0:3]
	v_mfma_f32_16x16x32_bf16 v[48:51], v[196:199], v[164:167], v[48:51]
	v_mfma_f32_16x16x32_bf16 v[40:43], v[204:207], v[164:167], v[40:43]
	v_mfma_f32_16x16x32_bf16 v[32:35], v[196:199], v[172:175], v[32:35]
	v_mfma_f32_16x16x32_bf16 v[24:27], v[204:207], v[172:175], v[24:27]
	v_mfma_f32_16x16x32_bf16 v[16:19], v[196:199], v[180:183], v[16:19]
	v_mfma_f32_16x16x32_bf16 v[8:11], v[204:207], v[180:183], v[8:11]
	v_mfma_f32_16x16x32_bf16 v[4:7], v[196:199], v[188:191], v[4:7]
	v_mfma_f32_16x16x32_bf16 v[0:3], v[204:207], v[188:191], v[0:3]
	s_add_i32 s0, s88, 0x100
	s_barrier
	ds_read_b128 v[140:143], v208 offset:32768
	ds_read_b128 v[148:151], v208 offset:33792
	ds_read_b128 v[152:155], v208 offset:34816
	ds_read_b128 v[156:159], v208 offset:35840
	s_add_u32 s70, s70, 0x80000
	s_addc_u32 s71, s71, 0
	s_mov_b32 m0, s37
	ds_read_b128 v[160:163], v139 offset:32768
	ds_read_b128 v[164:167], v139 offset:33792
	ds_read_b128 v[168:171], v139 offset:34816
	ds_read_b128 v[172:175], v139 offset:35840
	ds_read_b128 v[176:179], v139 offset:36864
	ds_read_b128 v[180:183], v139 offset:37888
	ds_read_b128 v[184:187], v139 offset:38912
	ds_read_b128 v[188:191], v139 offset:39936
	global_load_lds_dwordx4 v132, s[70:71]
	s_mov_b32 m0, s38
	s_nop 0
	global_load_lds_dwordx4 v130, s[70:71]
	s_waitcnt lgkmcnt(8)
	s_barrier
	s_waitcnt lgkmcnt(0)
	v_mfma_f32_16x16x32_bf16 v[124:127], v[140:143], v[160:163], v[124:127]
	v_mfma_f32_16x16x32_bf16 v[120:123], v[152:155], v[160:163], v[120:123]
	v_mfma_f32_16x16x32_bf16 v[116:119], v[140:143], v[168:171], v[116:119]
	v_mfma_f32_16x16x32_bf16 v[108:111], v[152:155], v[168:171], v[108:111]
	v_mfma_f32_16x16x32_bf16 v[100:103], v[140:143], v[176:179], v[100:103]
	v_mfma_f32_16x16x32_bf16 v[92:95], v[152:155], v[176:179], v[92:95]
	v_mfma_f32_16x16x32_bf16 v[84:87], v[140:143], v[184:187], v[84:87]
	v_mfma_f32_16x16x32_bf16 v[76:79], v[152:155], v[184:187], v[76:79]
	v_mfma_f32_16x16x32_bf16 v[124:127], v[148:151], v[164:167], v[124:127]
	v_mfma_f32_16x16x32_bf16 v[120:123], v[156:159], v[164:167], v[120:123]
	v_mfma_f32_16x16x32_bf16 v[116:119], v[148:151], v[172:175], v[116:119]
	v_mfma_f32_16x16x32_bf16 v[108:111], v[156:159], v[172:175], v[108:111]
	v_mfma_f32_16x16x32_bf16 v[100:103], v[148:151], v[180:183], v[100:103]
	v_mfma_f32_16x16x32_bf16 v[92:95], v[156:159], v[180:183], v[92:95]
	v_mfma_f32_16x16x32_bf16 v[84:87], v[148:151], v[188:191], v[84:87]
	v_mfma_f32_16x16x32_bf16 v[76:79], v[156:159], v[188:191], v[76:79]
	s_barrier
	s_add_i32 s1, s89, 0x100
	s_add_i32 s0, s0, s24
	ds_read_b128 v[192:195], v208 offset:49152
	ds_read_b128 v[196:199], v208 offset:50176
	ds_read_b128 v[200:203], v208 offset:51200
	ds_read_b128 v[204:207], v208 offset:52224
	s_mov_b32 m0, s0
	s_nop 0
	global_load_lds_dwordx4 v146, s[66:67]
	s_add_i32 m0, s0, 0x2000
	s_nop 0
	global_load_lds_dwordx4 v128, s[66:67]
	s_barrier
	s_waitcnt lgkmcnt(0)
	v_mfma_f32_16x16x32_bf16 v[112:115], v[192:195], v[160:163], v[112:115]
	v_mfma_f32_16x16x32_bf16 v[104:107], v[200:203], v[160:163], v[104:107]
	v_mfma_f32_16x16x32_bf16 v[96:99], v[192:195], v[168:171], v[96:99]
	v_mfma_f32_16x16x32_bf16 v[88:91], v[200:203], v[168:171], v[88:91]
	v_mfma_f32_16x16x32_bf16 v[80:83], v[192:195], v[176:179], v[80:83]
	v_mfma_f32_16x16x32_bf16 v[72:75], v[200:203], v[176:179], v[72:75]
	v_mfma_f32_16x16x32_bf16 v[68:71], v[192:195], v[184:187], v[68:71]
	v_mfma_f32_16x16x32_bf16 v[64:67], v[200:203], v[184:187], v[64:67]
	v_mfma_f32_16x16x32_bf16 v[112:115], v[196:199], v[164:167], v[112:115]
	v_mfma_f32_16x16x32_bf16 v[104:107], v[204:207], v[164:167], v[104:107]
	v_mfma_f32_16x16x32_bf16 v[96:99], v[196:199], v[172:175], v[96:99]
	v_mfma_f32_16x16x32_bf16 v[88:91], v[204:207], v[172:175], v[88:91]
	v_mfma_f32_16x16x32_bf16 v[80:83], v[196:199], v[180:183], v[80:83]
	v_mfma_f32_16x16x32_bf16 v[72:75], v[204:207], v[180:183], v[72:75]
	v_mfma_f32_16x16x32_bf16 v[68:71], v[196:199], v[188:191], v[68:71]
	v_mfma_f32_16x16x32_bf16 v[64:67], v[204:207], v[188:191], v[64:67]
	s_mov_b32 m0, s75
	s_barrier
	ds_read_b128 v[160:163], v139 offset:49152
	ds_read_b128 v[164:167], v139 offset:50176
	ds_read_b128 v[168:171], v139 offset:51200
	ds_read_b128 v[172:175], v139 offset:52224
	ds_read_b128 v[176:179], v139 offset:53248
	ds_read_b128 v[180:183], v139 offset:54272
	ds_read_b128 v[184:187], v139 offset:55296
	ds_read_b128 v[188:191], v139 offset:56320
	global_load_lds_dwordx4 v132, s[68:69]
	s_mov_b32 m0, s76
	s_nop 0
	global_load_lds_dwordx4 v130, s[68:69]
	s_barrier
	s_waitcnt lgkmcnt(0)
	v_mfma_f32_16x16x32_bf16 v[60:63], v[140:143], v[160:163], v[60:63]
	v_mfma_f32_16x16x32_bf16 v[56:59], v[152:155], v[160:163], v[56:59]
	v_mfma_f32_16x16x32_bf16 v[52:55], v[140:143], v[168:171], v[52:55]
	v_mfma_f32_16x16x32_bf16 v[44:47], v[152:155], v[168:171], v[44:47]
	v_mfma_f32_16x16x32_bf16 v[36:39], v[140:143], v[176:179], v[36:39]
	v_mfma_f32_16x16x32_bf16 v[28:31], v[152:155], v[176:179], v[28:31]
	v_mfma_f32_16x16x32_bf16 v[20:23], v[140:143], v[184:187], v[20:23]
	v_mfma_f32_16x16x32_bf16 v[12:15], v[152:155], v[184:187], v[12:15]
	v_mfma_f32_16x16x32_bf16 v[60:63], v[148:151], v[164:167], v[60:63]
	v_mfma_f32_16x16x32_bf16 v[56:59], v[156:159], v[164:167], v[56:59]
	v_mfma_f32_16x16x32_bf16 v[52:55], v[148:151], v[172:175], v[52:55]
	v_mfma_f32_16x16x32_bf16 v[44:47], v[156:159], v[172:175], v[44:47]
	v_mfma_f32_16x16x32_bf16 v[36:39], v[148:151], v[180:183], v[36:39]
	v_mfma_f32_16x16x32_bf16 v[28:31], v[156:159], v[180:183], v[28:31]
	v_mfma_f32_16x16x32_bf16 v[20:23], v[148:151], v[188:191], v[20:23]
	v_mfma_f32_16x16x32_bf16 v[12:15], v[156:159], v[188:191], v[12:15]
	s_barrier
; #define G_STAGE(bufoff, gbase, voff) do { _Pragma("unroll") for (int _i = 0; _i < 2; ++_i) \
;         __builtin_amdgcn_global_load_lds((const unsigned*)((const char*)(gbase) + (voff)[_i]), (LAS unsigned*)(lds + (bufoff) + ldsw + _i * 8192), 16, 0, 0); } while (0)
; #define G_MMA(ai, bj, At, Bt) do { __builtin_amdgcn_s_setprio(1); _Pragma("unroll") for (int m = 0; m < 4; ++m) _Pragma("unroll") for (int n = 0; n < 2; ++n) _Pragma("unroll") for (int k = 0; k < 2; ++k) \
;         acc[ai][bj][m][n] = __builtin_amdgcn_mfma_f32_16x16x32_bf16(Bt[n][k], At[m][k], acc[ai][bj][m][n], 0, 0, 0); __builtin_amdgcn_s_setprio(0); } while (0)
; #define G_WAIT_V(n) asm volatile("s_waitcnt vmcnt(" #n ")" ::: "memory")
; #define G_BAR __builtin_amdgcn_s_barrier()
; template <class J>
; DI void gemm_phase(LAS unsigned char* lds, const J& job) {
;     ...
;     for (int t = 0; t < nt; t += 2) {
;       const bool last = (t == nt - 2);
;       const char* a1 = cA + G_KT(t + 1);
;       const char* a2 = last ? nA + G_KT(0) : cA + G_KT(t + 2); const char* b2 = last ? nB + G_KT(0) : cB + G_KT(t + 2);
;       const char* a3 = last ? nA + G_KT(1) : cA + G_KT(t + 3); const char* b3 = last ? nB + G_KT(1) : cB + G_KT(t + 3);
;     ...
;       G_STAGE(G_SB(1, 1), b3 + hstepB, voffB);
;       G_WAIT_V(6); G_BAR; G_MMA(1, 1, At, B1); G_BAR;
	s_add_u32 s66, s66, 0x20000
	s_addc_u32 s67, s67, 0
	s_add_i32 s0, s1, s24
	s_mov_b32 m0, s0
	s_nop 0
	global_load_lds_dwordx4 v146, s[66:67]
	s_add_i32 m0, s0, 0x2000
	s_nop 0
	global_load_lds_dwordx4 v128, s[66:67]
	s_add_i32 s6, s6, 2
	s_addk_i32 s56, 0x100
	s_addk_i32 s7, 0x100
	s_add_i32 s1, s56, 0xffffff80
	s_and_b32 s0, s7, 0x380
	s_and_b32 s1, s1, 0x380
	s_add_u32 s57, s64, s1
	s_addc_u32 s66, s65, 0
	s_add_u32 s1, s62, s1
	s_addc_u32 s67, s63, 0
	s_and_b32 s68, s56, 0x380
	s_add_u32 s80, s64, s68
	s_addc_u32 s69, s65, 0
	s_add_u32 s97, s62, s68
	s_addc_u32 vcc_lo, s63, 0
	s_cmp_eq_u32 s6, 4
	s_cselect_b32 s71, s83, s66
	s_cselect_b32 s70, s47, s57
	s_cselect_b32 s73, s87, s67
	s_cselect_b32 s72, s86, s1
	s_cselect_b32 s69, s94, s69
	s_cselect_b32 s68, s33, s80
	s_cselect_b32 s67, s5, vcc_lo
	s_cselect_b32 s66, s96, s97
	s_add_i32 s1, s84, 0x100
	s_add_u32 vcc_lo, s9, s0
	s_addc_u32 vcc_hi, s17, 0
	s_waitcnt vmcnt(6)
	s_barrier
	v_mfma_f32_16x16x32_bf16 v[48:51], v[192:195], v[160:163], v[48:51]
	v_mfma_f32_16x16x32_bf16 v[40:43], v[200:203], v[160:163], v[40:43]
	v_mfma_f32_16x16x32_bf16 v[32:35], v[192:195], v[168:171], v[32:35]
	v_mfma_f32_16x16x32_bf16 v[24:27], v[200:203], v[168:171], v[24:27]
	v_mfma_f32_16x16x32_bf16 v[16:19], v[192:195], v[176:179], v[16:19]
	v_mfma_f32_16x16x32_bf16 v[8:11], v[200:203], v[176:179], v[8:11]
	v_mfma_f32_16x16x32_bf16 v[4:7], v[192:195], v[184:187], v[4:7]
	v_mfma_f32_16x16x32_bf16 v[0:3], v[200:203], v[184:187], v[0:3]
	v_mfma_f32_16x16x32_bf16 v[48:51], v[196:199], v[164:167], v[48:51]
	v_mfma_f32_16x16x32_bf16 v[40:43], v[204:207], v[164:167], v[40:43]
	v_mfma_f32_16x16x32_bf16 v[32:35], v[196:199], v[172:175], v[32:35]
	v_mfma_f32_16x16x32_bf16 v[24:27], v[204:207], v[172:175], v[24:27]
	v_mfma_f32_16x16x32_bf16 v[16:19], v[196:199], v[180:183], v[16:19]
	v_mfma_f32_16x16x32_bf16 v[8:11], v[204:207], v[180:183], v[8:11]
	v_mfma_f32_16x16x32_bf16 v[4:7], v[196:199], v[188:191], v[4:7]
	v_mfma_f32_16x16x32_bf16 v[0:3], v[204:207], v[188:191], v[0:3]
	s_cmp_gt_u32 s6, 5
	s_barrier
	s_cbranch_scc0 .LBB0_104
; DI unsigned pk2(float lo, float hi) { unsigned r; asm("v_cvt_pk_bf16_f32 %0, %1, %2" : "=v"(r) : "v"(lo), "v"(hi)); return r; }
; #define G_WAIT_V(n) asm volatile("s_waitcnt vmcnt(" #n ")" ::: "memory")
; #define G_BAR __builtin_amdgcn_s_barrier()
; template <class J>
; DI void gemm_phase(LAS unsigned char* lds, const J& job) {
;     ...
;     if (!has_next) break;
; #pragma unroll
;     for (int a = 0; a < 2; ++a)
; #pragma unroll
;       for (int b = 0; b < 2; ++b)
; #pragma unroll
;         for (int m = 0; m < 4; ++m)
; #pragma unroll
;           for (int n = 0; n < 2; ++n) acc[a][b][m][n] = (f32x4){0.f, 0.f, 0.f, 0.f};
;     cur = nxt; cA = nA; cB = nB; ++ui;
;   }
;   G_WAIT_V(0);
;   if (wr == 0) G_BAR;
;   DI void epi(const Acc& acc, const Unit& u, int wr, int wc, int fr, int fq) const {
; #pragma unroll
;     for (int ai = 0; ai < 2; ++ai)
; #pragma unroll
;       for (int m = 0; m < 4; ++m) {
;         const int row = u.pm * 256 + ai * HALF + wr * 64 + m * 16 + fr;
; #pragma unroll
;         for (int bj = 0; bj < 2; ++bj) {
;           const int col = u.pn * 256 + bj * HALF + wc * 32 + 8 * fq;
;           const f32x4 v0 = acc[ai][bj][m][0], v1 = acc[ai][bj][m][1];
;           u32x4 o; o.x = pk2(v0.x, v0.y); o.y = pk2(v0.z, v0.w); o.z = pk2(v1.x, v1.y); o.w = pk2(v1.z, v1.w);
;           *(u32x4*)(Z + (size_t)row * NGATE + col) = o;
;         }
;       }
;   }
	v_mov_b32_e32 v135, v137
	v_mov_b32_e32 v134, v136
	s_lshl_b32 s0, s22, 8
	s_add_i32 s0, s0, s44
	v_add_u32_e32 v134, s0, v134
	s_lshl_b32 s0, s46, 8
	s_or_b32 s0, s0, s45
	v_cvt_pk_bf16_f32 v68, v68, v69
	v_cvt_pk_bf16_f32 v69, v70, v71
	v_cvt_pk_bf16_f32 v70, v64, v65
	v_add_u32_e32 v64, 0x80, v134
	v_lshl_add_u32 v140, v135, 3, s0
	v_ashrrev_i32_e32 v135, 31, v134
	v_ashrrev_i32_e32 v65, 31, v64
	v_lshlrev_b64 v[142:143], 14, v[134:135]
	v_ashrrev_i32_e32 v141, 31, v140
	v_lshlrev_b64 v[64:65], 14, v[64:65]
	v_cvt_pk_bf16_f32 v124, v124, v125
	v_cvt_pk_bf16_f32 v125, v126, v127
	v_cvt_pk_bf16_f32 v126, v120, v121
	v_cvt_pk_bf16_f32 v127, v122, v123
	v_lshl_add_u64 v[122:123], s[26:27], 0, v[142:143]
	v_lshlrev_b64 v[120:121], 1, v[140:141]
	v_cvt_pk_bf16_f32 v112, v112, v113
	v_cvt_pk_bf16_f32 v113, v114, v115
	v_cvt_pk_bf16_f32 v114, v104, v105
	v_add_u32_e32 v104, 16, v134
	v_cvt_pk_bf16_f32 v60, v60, v61
	v_cvt_pk_bf16_f32 v61, v62, v63
	v_cvt_pk_bf16_f32 v62, v56, v57
	v_lshl_add_u64 v[56:57], s[26:27], 0, v[64:65]
	v_cvt_pk_bf16_f32 v48, v48, v49
	v_cvt_pk_bf16_f32 v49, v50, v51
	v_cvt_pk_bf16_f32 v50, v40, v41
	v_add_u32_e32 v40, 0x90, v134
	v_lshl_add_u64 v[122:123], v[122:123], 0, v[120:121]
	v_ashrrev_i32_e32 v105, 31, v104
	v_lshl_add_u64 v[56:57], v[56:57], 0, v[120:121]
	v_ashrrev_i32_e32 v41, 31, v40
	v_cvt_pk_bf16_f32 v115, v106, v107
	global_store_dwordx4 v[122:123], v[112:115], off offset:256
	v_cvt_pk_bf16_f32 v51, v42, v43
	global_store_dwordx4 v[56:57], v[48:51], off offset:256
	v_cvt_pk_bf16_f32 v106, v108, v109
	v_cvt_pk_bf16_f32 v96, v96, v97
	v_cvt_pk_bf16_f32 v97, v98, v99
	s_nop 0
	v_lshlrev_b64 v[112:113], 14, v[104:105]
	v_lshl_add_u64 v[108:109], s[26:27], 0, v[112:113]
	v_lshlrev_b64 v[48:49], 14, v[40:41]
	v_cvt_pk_bf16_f32 v98, v88, v89
	v_add_u32_e32 v88, 32, v134
	v_cvt_pk_bf16_f32 v42, v44, v45
	v_lshl_add_u64 v[44:45], s[26:27], 0, v[48:49]
	v_cvt_pk_bf16_f32 v32, v32, v33
	v_cvt_pk_bf16_f32 v33, v34, v35
	v_cvt_pk_bf16_f32 v34, v24, v25
	v_add_u32_e32 v24, 0xa0, v134
	v_lshl_add_u64 v[108:109], v[108:109], 0, v[120:121]
	v_ashrrev_i32_e32 v89, 31, v88
	v_lshl_add_u64 v[44:45], v[44:45], 0, v[120:121]
	v_ashrrev_i32_e32 v25, 31, v24
	v_cvt_pk_bf16_f32 v99, v90, v91
	global_store_dwordx4 v[108:109], v[96:99], off offset:256
	v_cvt_pk_bf16_f32 v35, v26, v27
	global_store_dwordx4 v[44:45], v[32:35], off offset:256
	v_cvt_pk_bf16_f32 v90, v92, v93
	v_cvt_pk_bf16_f32 v80, v80, v81
	v_cvt_pk_bf16_f32 v81, v82, v83
	s_nop 0
	v_lshlrev_b64 v[96:97], 14, v[88:89]
	v_lshl_add_u64 v[92:93], s[26:27], 0, v[96:97]
	v_lshlrev_b64 v[32:33], 14, v[24:25]
	v_cvt_pk_bf16_f32 v82, v72, v73
	v_add_u32_e32 v72, 48, v134
	v_cvt_pk_bf16_f32 v26, v28, v29
	v_lshl_add_u64 v[28:29], s[26:27], 0, v[32:33]
	v_cvt_pk_bf16_f32 v16, v16, v17
	v_cvt_pk_bf16_f32 v17, v18, v19
	v_cvt_pk_bf16_f32 v18, v8, v9
	v_add_u32_e32 v8, 0xb0, v134
	v_lshl_add_u64 v[92:93], v[92:93], 0, v[120:121]
	v_ashrrev_i32_e32 v73, 31, v72
	v_lshl_add_u64 v[28:29], v[28:29], 0, v[120:121]
	v_ashrrev_i32_e32 v9, 31, v8
	v_cvt_pk_bf16_f32 v83, v74, v75
	global_store_dwordx4 v[92:93], v[80:83], off offset:256
	v_cvt_pk_bf16_f32 v19, v10, v11
	global_store_dwordx4 v[28:29], v[16:19], off offset:256
	v_cvt_pk_bf16_f32 v74, v76, v77
	v_cvt_pk_bf16_f32 v10, v12, v13
	s_and_b64 vcc, exec, s[12:13]
	v_lshlrev_b64 v[80:81], 14, v[72:73]
	v_lshlrev_b64 v[16:17], 14, v[8:9]
	v_lshl_add_u64 v[76:77], s[26:27], 0, v[80:81]
	v_lshl_add_u64 v[12:13], s[26:27], 0, v[16:17]
	v_lshl_add_u64 v[76:77], v[76:77], 0, v[120:121]
	v_lshl_add_u64 v[12:13], v[12:13], 0, v[120:121]
	s_mov_b32 s46, s8
	s_mov_b32 s22, s16
	s_mov_b64 s[62:63], s[20:21]
	s_mov_b64 s[64:65], s[18:19]
	global_store_dwordx4 v[122:123], v[124:127], off
	v_cvt_pk_bf16_f32 v104, v116, v117
	v_cvt_pk_bf16_f32 v105, v118, v119
	v_cvt_pk_bf16_f32 v107, v110, v111
	global_store_dwordx4 v[108:109], v[104:107], off
	v_cvt_pk_bf16_f32 v88, v100, v101
	v_cvt_pk_bf16_f32 v89, v102, v103
	v_cvt_pk_bf16_f32 v91, v94, v95
	global_store_dwordx4 v[92:93], v[88:91], off
	v_cvt_pk_bf16_f32 v72, v84, v85
	v_cvt_pk_bf16_f32 v73, v86, v87
	v_cvt_pk_bf16_f32 v75, v78, v79
	global_store_dwordx4 v[76:77], v[72:75], off
	v_cvt_pk_bf16_f32 v71, v66, v67
	global_store_dwordx4 v[76:77], v[68:71], off offset:256
	v_cvt_pk_bf16_f32 v63, v58, v59
	global_store_dwordx4 v[56:57], v[60:63], off
	v_cvt_pk_bf16_f32 v40, v52, v53
	v_cvt_pk_bf16_f32 v41, v54, v55
	v_cvt_pk_bf16_f32 v43, v46, v47
	global_store_dwordx4 v[44:45], v[40:43], off
	v_cvt_pk_bf16_f32 v24, v36, v37
	v_cvt_pk_bf16_f32 v25, v38, v39
	v_cvt_pk_bf16_f32 v27, v30, v31
	global_store_dwordx4 v[28:29], v[24:27], off
	v_cvt_pk_bf16_f32 v8, v20, v21
	v_cvt_pk_bf16_f32 v9, v22, v23
	v_cvt_pk_bf16_f32 v11, v14, v15
	global_store_dwordx4 v[12:13], v[8:11], off
	v_cvt_pk_bf16_f32 v4, v4, v5
	v_cvt_pk_bf16_f32 v5, v6, v7
	v_cvt_pk_bf16_f32 v6, v0, v1
	v_cvt_pk_bf16_f32 v7, v2, v3
	global_store_dwordx4 v[12:13], v[4:7], off offset:256
	s_cbranch_vccz .LBB0_101
	s_setprio 0
	s_waitcnt vmcnt(0)
	v_readlane_b32 s44, v255, 6
	s_cmpk_gt_u32 s4, 0xff
	v_readlane_b32 s45, v255, 7
	s_cbranch_scc1 .LBB0_108
	s_barrier

;   DI const char* aptr(const Unit& u) const { return (const char*)(h + (size_t)u.pm * 256 * DM); }
;   DI const char* bptr(const Unit& u) const { return (const char*)(winT + (size_t)u.pn * 256 * DM); }
;   DI bool next(int i, Unit& u) const { const int L = i * G + c; if (L >= nunits) return false; u.kind = 0; decode_unit(L, 65, 32, u.pm, u.pn); return true; }
;   DI const char* aptr(const Unit& u) const { return (const char*)(y + (size_t)u.pm * 256 * DM + (u.pn >> 3) * 512); }
;   DI const char* bptr(const Unit& u) const { return (const char*)(wbT + (size_t)u.pn * 256 * 512); }
;   DI const char* aptr(const Unit& u) const { return (const char*)(h + (size_t)u.pm * 256 * DM); }
;   DI const char* bptr(const Unit& u) const { return (const char*)(wgT + (size_t)u.pn * 64 * DM); }
;   DI const char* aptr(const Unit& u) const { return (const char*)(mixed + (size_t)u.pm * 256 * DM); }
;   DI const char* bptr(const Unit& u) const { return (const char*)(woutT + (size_t)u.pn * 256 * DM); }
; template <class J>
; DI void gemm_phase(LAS unsigned char* lds, const J& job) {
;     ...
;     const bool has_next = job.next(ui + 1, nxt);
;     const char* nA = has_next ? job.aptr(nxt) : cA; const char* nB = has_next ? job.bptr(nxt) : cB;
;     for (int t = 0; t < nt; t += 2) {
;       const bool last = (t == nt - 2);
;       const char* a1 = cA + G_KT(t + 1);
;       const char* a2 = last ? nA + G_KT(0) : cA + G_KT(t + 2); const char* b2 = last ? nB + G_KT(0) : cB + G_KT(t + 2);
;       const char* a3 = last ? nA + G_KT(1) : cA + G_KT(t + 3); const char* b3 = last ? nB + G_KT(1) : cB + G_KT(t + 3);
;     ...
; #pragma unroll
;     for (int a = 0; a < 2; ++a)
; #pragma unroll
;       for (int b = 0; b < 2; ++b)
; #pragma unroll
;         for (int m = 0; m < 4; ++m)
; #pragma unroll
;           for (int n = 0; n < 2; ++n) acc[a][b][m][n] = (f32x4){0.f, 0.f, 0.f, 0.f};
;     cur = nxt; cA = nA; cB = nB; ++ui;
.LBB0_281:
	s_ashr_i32 s19, s18, 31
	s_lshl_b64 s[6:7], s[18:19], 20
	s_add_u32 s22, s58, s6
	s_addc_u32 s23, s59, s7
	s_ashr_i32 s21, s20, 31
	s_lshl_b64 s[6:7], s[20:21], 20
	s_add_u32 s62, s12, s6
	s_addc_u32 s63, s13, s7
	s_add_u32 s9, s68, 0x80000
	s_addc_u32 s19, s69, 0
	s_and_b64 s[6:7], s[70:71], exec
	s_cselect_b32 s7, s22, s68
	s_cselect_b32 s0, s63, s67
	s_cselect_b32 s1, s62, s66
	s_cselect_b32 s6, s23, s69
	s_add_u32 s21, s7, s14
	s_addc_u32 s46, s6, 0
	s_add_u32 s47, s1, s14
	s_addc_u32 s96, s0, 0
	s_add_u32 s33, s7, s44
	s_addc_u32 s97, s6, 0
	s_add_u32 vcc_lo, s1, s44
	v_mov_b32_e32 v0, 0
	s_addc_u32 vcc_hi, s0, 0
	s_mov_b32 s6, -2
	s_mov_b32 s7, s94
	s_mov_b32 s56, s87
	v_mov_b32_e32 v1, v0
	v_mov_b32_e32 v2, v0
	v_mov_b32_e32 v3, v0
	v_mov_b32_e32 v4, v0
	v_mov_b32_e32 v5, v0
	v_mov_b32_e32 v6, v0
	v_mov_b32_e32 v7, v0
	v_mov_b32_e32 v16, v0
	v_mov_b32_e32 v17, v0
	v_mov_b32_e32 v18, v0
	v_mov_b32_e32 v19, v0
	v_mov_b32_e32 v20, v0
	v_mov_b32_e32 v21, v0
	v_mov_b32_e32 v22, v0
	v_mov_b32_e32 v23, v0
	v_mov_b32_e32 v32, v0
	v_mov_b32_e32 v33, v0
	v_mov_b32_e32 v34, v0
	v_mov_b32_e32 v35, v0
	v_mov_b32_e32 v36, v0
	v_mov_b32_e32 v37, v0
	v_mov_b32_e32 v38, v0
	v_mov_b32_e32 v39, v0
	v_mov_b32_e32 v48, v0
	v_mov_b32_e32 v49, v0
	v_mov_b32_e32 v50, v0
	v_mov_b32_e32 v51, v0
	v_mov_b32_e32 v52, v0
	v_mov_b32_e32 v53, v0
	v_mov_b32_e32 v54, v0
	v_mov_b32_e32 v55, v0
	v_mov_b32_e32 v8, v0
	v_mov_b32_e32 v9, v0
	v_mov_b32_e32 v10, v0
	v_mov_b32_e32 v11, v0
	v_mov_b32_e32 v12, v0
	v_mov_b32_e32 v13, v0
	v_mov_b32_e32 v14, v0
	v_mov_b32_e32 v15, v0
	v_mov_b32_e32 v24, v0
	v_mov_b32_e32 v25, v0
	v_mov_b32_e32 v26, v0
	v_mov_b32_e32 v27, v0
	v_mov_b32_e32 v28, v0
	v_mov_b32_e32 v29, v0
	v_mov_b32_e32 v30, v0
	v_mov_b32_e32 v31, v0
	v_mov_b32_e32 v40, v0
	v_mov_b32_e32 v41, v0
	v_mov_b32_e32 v42, v0
	v_mov_b32_e32 v43, v0
	v_mov_b32_e32 v44, v0
	v_mov_b32_e32 v45, v0
	v_mov_b32_e32 v46, v0
	v_mov_b32_e32 v47, v0
	v_mov_b32_e32 v56, v0
	v_mov_b32_e32 v57, v0
	v_mov_b32_e32 v58, v0
	v_mov_b32_e32 v59, v0
	v_mov_b32_e32 v60, v0
	v_mov_b32_e32 v61, v0
	v_mov_b32_e32 v62, v0
	v_mov_b32_e32 v63, v0
	v_mov_b32_e32 v64, v0
	v_mov_b32_e32 v65, v0
	v_mov_b32_e32 v66, v0
	v_mov_b32_e32 v67, v0
	v_mov_b32_e32 v68, v0
	v_mov_b32_e32 v69, v0
	v_mov_b32_e32 v70, v0
	v_mov_b32_e32 v71, v0
	v_mov_b32_e32 v80, v0
	v_mov_b32_e32 v81, v0
	v_mov_b32_e32 v82, v0
	v_mov_b32_e32 v83, v0
	v_mov_b32_e32 v84, v0
	v_mov_b32_e32 v85, v0
	v_mov_b32_e32 v86, v0
	v_mov_b32_e32 v87, v0
	v_mov_b32_e32 v96, v0
	v_mov_b32_e32 v97, v0
	v_mov_b32_e32 v98, v0
	v_mov_b32_e32 v99, v0
	v_mov_b32_e32 v100, v0
	v_mov_b32_e32 v101, v0
	v_mov_b32_e32 v102, v0
	v_mov_b32_e32 v103, v0
	v_mov_b32_e32 v112, v0
	v_mov_b32_e32 v113, v0
	v_mov_b32_e32 v114, v0
	v_mov_b32_e32 v115, v0
	v_mov_b32_e32 v116, v0
	v_mov_b32_e32 v117, v0
	v_mov_b32_e32 v118, v0
	v_mov_b32_e32 v119, v0
	v_mov_b32_e32 v72, v0
	v_mov_b32_e32 v73, v0
	v_mov_b32_e32 v74, v0
	v_mov_b32_e32 v75, v0
	v_mov_b32_e32 v76, v0
	v_mov_b32_e32 v77, v0
	v_mov_b32_e32 v78, v0
	v_mov_b32_e32 v79, v0
	v_mov_b32_e32 v88, v0
	v_mov_b32_e32 v89, v0
	v_mov_b32_e32 v90, v0
	v_mov_b32_e32 v91, v0
	v_mov_b32_e32 v92, v0
	v_mov_b32_e32 v93, v0
	v_mov_b32_e32 v94, v0
	v_mov_b32_e32 v95, v0
	v_mov_b32_e32 v104, v0
	v_mov_b32_e32 v105, v0
	v_mov_b32_e32 v106, v0
	v_mov_b32_e32 v107, v0
	v_mov_b32_e32 v108, v0
	v_mov_b32_e32 v109, v0
	v_mov_b32_e32 v110, v0
	v_mov_b32_e32 v111, v0
	v_mov_b32_e32 v120, v0
	v_mov_b32_e32 v121, v0
	v_mov_b32_e32 v122, v0
	v_mov_b32_e32 v123, v0
	v_mov_b32_e32 v124, v0
	v_mov_b32_e32 v125, v0
	v_mov_b32_e32 v126, v0
	v_mov_b32_e32 v127, v0
	s_add_i32 s1, s56, 0xffffff80
	s_and_b32 s0, s7, 0xf80
	s_and_b32 s1, s1, 0xf00
	s_add_u32 s10, s68, s1
	s_addc_u32 s11, s69, 0
	s_add_u32 s1, s66, s1
	s_addc_u32 s57, s67, 0
	s_and_b32 s70, s56, 0xf80
	s_add_u32 s71, s68, s70
	s_addc_u32 s72, s69, 0
	s_add_u32 s70, s66, s70
	s_addc_u32 s80, s67, 0
	s_cmp_eq_u32 s6, 28
	s_cselect_b32 s75, s46, s11
	s_cselect_b32 s74, s21, s10
	s_cselect_b32 s77, s96, s57
	s_cselect_b32 s76, s47, s1
	s_cselect_b32 s73, s97, s72
	s_cselect_b32 s72, s33, s71
	s_cselect_b32 s71, vcc_hi, s80
	s_cselect_b32 s70, vcc_lo, s70
	s_add_i32 s1, s84, 0x100
	s_add_u32 s10, s9, s0
	s_addc_u32 s11, s19, 0
; #define G_STAGE(bufoff, gbase, voff) do { _Pragma("unroll") for (int _i = 0; _i < 2; ++_i) \
;         __builtin_amdgcn_global_load_lds((const unsigned*)((const char*)(gbase) + (voff)[_i]), (LAS unsigned*)(lds + (bufoff) + ldsw + _i * 8192), 16, 0, 0); } while (0)
; #define G_LDA(dst, b, h) do { _Pragma("unroll") for (int m = 0; m < 4; ++m) _Pragma("unroll") for (int k = 0; k < 2; ++k) dst[m][k] = *(const LAS bf16x8*)(lds + G_SA(b, h) + aoff + m * 2048 + k * 1024); } while (0)
; #define G_LDB(dst, b, h) do { _Pragma("unroll") for (int n = 0; n < 2; ++n) _Pragma("unroll") for (int k = 0; k < 2; ++k) dst[n][k] = *(const LAS bf16x8*)(lds + G_SB(b, h) + boff + n * 2048 + k * 1024); } while (0)
; #define G_MMA(ai, bj, At, Bt) do { __builtin_amdgcn_s_setprio(1); _Pragma("unroll") for (int m = 0; m < 4; ++m) _Pragma("unroll") for (int n = 0; n < 2; ++n) _Pragma("unroll") for (int k = 0; k < 2; ++k) \
;         acc[ai][bj][m][n] = __builtin_amdgcn_mfma_f32_16x16x32_bf16(Bt[n][k], At[m][k], acc[ai][bj][m][n], 0, 0, 0); __builtin_amdgcn_s_setprio(0); } while (0)
; #define G_WAIT_V(n) asm volatile("s_waitcnt vmcnt(" #n ")" ::: "memory")
; #define G_WAIT_L(n) asm volatile("s_waitcnt lgkmcnt(" #n ")" ::: "memory")
; #define G_BAR __builtin_amdgcn_s_barrier()
; #define G_SCHED __builtin_amdgcn_sched_barrier(0)
; template <class J>
; DI void gemm_phase(LAS unsigned char* lds, const J& job) {
;     ...
;       G_LDB(B0, 0, 0); G_SCHED; G_LDA(At, 0, 0); G_STAGE(G_SA(1, 1), a1 + hstepA, voffA);
;       G_WAIT_L(8); G_BAR; G_WAIT_L(0); G_MMA(0, 0, At, B0); G_BAR; G_SCHED;
;       G_LDB(B1, 0, 1); G_STAGE(G_SB(0, 0), b2, voffB);
;       G_BAR; G_WAIT_L(0); G_MMA(0, 1, At, B1); G_BAR;
;       G_LDA(At, 0, 1); G_STAGE(G_SA(0, 0), a2, voffA);
;       G_BAR; G_WAIT_L(0); G_MMA(1, 0, At, B0); G_BAR; G_SCHED;
;       G_STAGE(G_SB(0, 1), b2 + hstepB, voffB);
;       G_WAIT_V(6); G_BAR; G_MMA(1, 1, At, B1); G_BAR;
.LBB0_282:
	ds_read_b128 v[134:137], v208
	ds_read_b128 v[138:141], v208 offset:1024
	ds_read_b128 v[152:155], v208 offset:2048
	ds_read_b128 v[156:159], v208 offset:3072
	s_add_i32 m0, s15, 0xc000
	ds_read_b128 v[160:163], v151
	ds_read_b128 v[164:167], v151 offset:1024
	ds_read_b128 v[168:171], v151 offset:2048
	ds_read_b128 v[172:175], v151 offset:3072
	ds_read_b128 v[176:179], v151 offset:4096
	ds_read_b128 v[180:183], v151 offset:5120
	ds_read_b128 v[184:187], v151 offset:6144
	ds_read_b128 v[188:191], v151 offset:7168
	global_load_lds_dwordx4 v128, s[10:11]
	s_add_i32 m0, s15, 0xe000
	s_nop 0
	global_load_lds_dwordx4 v130, s[10:11]
	s_waitcnt lgkmcnt(8)
	s_barrier
	s_waitcnt lgkmcnt(0)
	v_mfma_f32_16x16x32_bf16 v[124:127], v[134:137], v[160:163], v[124:127]
	v_mfma_f32_16x16x32_bf16 v[120:123], v[152:155], v[160:163], v[120:123]
	v_mfma_f32_16x16x32_bf16 v[108:111], v[134:137], v[168:171], v[108:111]
	v_mfma_f32_16x16x32_bf16 v[104:107], v[152:155], v[168:171], v[104:107]
	v_mfma_f32_16x16x32_bf16 v[92:95], v[134:137], v[176:179], v[92:95]
	v_mfma_f32_16x16x32_bf16 v[88:91], v[152:155], v[176:179], v[88:91]
	v_mfma_f32_16x16x32_bf16 v[76:79], v[134:137], v[184:187], v[76:79]
	v_mfma_f32_16x16x32_bf16 v[72:75], v[152:155], v[184:187], v[72:75]
	v_mfma_f32_16x16x32_bf16 v[124:127], v[138:141], v[164:167], v[124:127]
	v_mfma_f32_16x16x32_bf16 v[120:123], v[156:159], v[164:167], v[120:123]
	v_mfma_f32_16x16x32_bf16 v[108:111], v[138:141], v[172:175], v[108:111]
	v_mfma_f32_16x16x32_bf16 v[104:107], v[156:159], v[172:175], v[104:107]
	v_mfma_f32_16x16x32_bf16 v[92:95], v[138:141], v[180:183], v[92:95]
	v_mfma_f32_16x16x32_bf16 v[88:91], v[156:159], v[180:183], v[88:91]
	v_mfma_f32_16x16x32_bf16 v[76:79], v[138:141], v[188:191], v[76:79]
	v_mfma_f32_16x16x32_bf16 v[72:75], v[156:159], v[188:191], v[72:75]
	s_barrier
	s_add_i32 s0, s85, 0x100
	s_add_i32 s1, s1, s5
	ds_read_b128 v[192:195], v208 offset:16384
	ds_read_b128 v[196:199], v208 offset:17408
	ds_read_b128 v[200:203], v208 offset:18432
	ds_read_b128 v[204:207], v208 offset:19456
	s_mov_b32 m0, s1
	s_nop 0
	global_load_lds_dwordx4 v146, s[76:77]
	s_add_i32 m0, s1, 0x2000
	s_nop 0
	global_load_lds_dwordx4 v132, s[76:77]
	s_barrier
	s_waitcnt lgkmcnt(0)
	v_mfma_f32_16x16x32_bf16 v[116:119], v[192:195], v[160:163], v[116:119]
	v_mfma_f32_16x16x32_bf16 v[112:115], v[200:203], v[160:163], v[112:115]
	v_mfma_f32_16x16x32_bf16 v[100:103], v[192:195], v[168:171], v[100:103]
	v_mfma_f32_16x16x32_bf16 v[96:99], v[200:203], v[168:171], v[96:99]
	v_mfma_f32_16x16x32_bf16 v[84:87], v[192:195], v[176:179], v[84:87]
	v_mfma_f32_16x16x32_bf16 v[80:83], v[200:203], v[176:179], v[80:83]
	v_mfma_f32_16x16x32_bf16 v[68:71], v[192:195], v[184:187], v[68:71]
	v_mfma_f32_16x16x32_bf16 v[64:67], v[200:203], v[184:187], v[64:67]
	v_mfma_f32_16x16x32_bf16 v[116:119], v[196:199], v[164:167], v[116:119]
	v_mfma_f32_16x16x32_bf16 v[112:115], v[204:207], v[164:167], v[112:115]
	v_mfma_f32_16x16x32_bf16 v[100:103], v[196:199], v[172:175], v[100:103]
	v_mfma_f32_16x16x32_bf16 v[96:99], v[204:207], v[172:175], v[96:99]
	v_mfma_f32_16x16x32_bf16 v[84:87], v[196:199], v[180:183], v[84:87]
	v_mfma_f32_16x16x32_bf16 v[80:83], v[204:207], v[180:183], v[80:83]
	v_mfma_f32_16x16x32_bf16 v[68:71], v[196:199], v[188:191], v[68:71]
	v_mfma_f32_16x16x32_bf16 v[64:67], v[204:207], v[188:191], v[64:67]
	s_mov_b32 m0, s15
	s_barrier
	ds_read_b128 v[160:163], v151 offset:16384
	ds_read_b128 v[164:167], v151 offset:17408
	ds_read_b128 v[168:171], v151 offset:18432
	ds_read_b128 v[172:175], v151 offset:19456
	ds_read_b128 v[176:179], v151 offset:20480
	ds_read_b128 v[180:183], v151 offset:21504
	ds_read_b128 v[184:187], v151 offset:22528
	ds_read_b128 v[188:191], v151 offset:23552
	global_load_lds_dwordx4 v128, s[74:75]
	s_mov_b32 m0, s24
	s_nop 0
	global_load_lds_dwordx4 v130, s[74:75]
	s_barrier
	s_waitcnt lgkmcnt(0)
	v_mfma_f32_16x16x32_bf16 v[60:63], v[134:137], v[160:163], v[60:63]
	v_mfma_f32_16x16x32_bf16 v[56:59], v[152:155], v[160:163], v[56:59]
	v_mfma_f32_16x16x32_bf16 v[44:47], v[134:137], v[168:171], v[44:47]
	v_mfma_f32_16x16x32_bf16 v[40:43], v[152:155], v[168:171], v[40:43]
	v_mfma_f32_16x16x32_bf16 v[28:31], v[134:137], v[176:179], v[28:31]
	v_mfma_f32_16x16x32_bf16 v[24:27], v[152:155], v[176:179], v[24:27]
	v_mfma_f32_16x16x32_bf16 v[12:15], v[134:137], v[184:187], v[12:15]
	v_mfma_f32_16x16x32_bf16 v[8:11], v[152:155], v[184:187], v[8:11]
	v_mfma_f32_16x16x32_bf16 v[60:63], v[138:141], v[164:167], v[60:63]
	v_mfma_f32_16x16x32_bf16 v[56:59], v[156:159], v[164:167], v[56:59]
	v_mfma_f32_16x16x32_bf16 v[44:47], v[138:141], v[172:175], v[44:47]
	v_mfma_f32_16x16x32_bf16 v[40:43], v[156:159], v[172:175], v[40:43]
	v_mfma_f32_16x16x32_bf16 v[28:31], v[138:141], v[180:183], v[28:31]
	v_mfma_f32_16x16x32_bf16 v[24:27], v[156:159], v[180:183], v[24:27]
	v_mfma_f32_16x16x32_bf16 v[12:15], v[138:141], v[188:191], v[12:15]
	v_mfma_f32_16x16x32_bf16 v[8:11], v[156:159], v[188:191], v[8:11]
	s_barrier
	s_add_u32 s10, s76, 0x80000
	s_addc_u32 s11, s77, 0
	s_add_i32 s0, s0, s5
	s_mov_b32 m0, s0
	s_nop 0
	global_load_lds_dwordx4 v146, s[10:11]
	s_add_i32 m0, s0, 0x2000
	s_nop 0
	global_load_lds_dwordx4 v132, s[10:11]
	s_waitcnt vmcnt(6)
	s_barrier
; #define G_STAGE(bufoff, gbase, voff) do { _Pragma("unroll") for (int _i = 0; _i < 2; ++_i) \
;         __builtin_amdgcn_global_load_lds((const unsigned*)((const char*)(gbase) + (voff)[_i]), (LAS unsigned*)(lds + (bufoff) + ldsw + _i * 8192), 16, 0, 0); } while (0)
; #define G_LDA(dst, b, h) do { _Pragma("unroll") for (int m = 0; m < 4; ++m) _Pragma("unroll") for (int k = 0; k < 2; ++k) dst[m][k] = *(const LAS bf16x8*)(lds + G_SA(b, h) + aoff + m * 2048 + k * 1024); } while (0)
; #define G_LDB(dst, b, h) do { _Pragma("unroll") for (int n = 0; n < 2; ++n) _Pragma("unroll") for (int k = 0; k < 2; ++k) dst[n][k] = *(const LAS bf16x8*)(lds + G_SB(b, h) + boff + n * 2048 + k * 1024); } while (0)
; #define G_MMA(ai, bj, At, Bt) do { __builtin_amdgcn_s_setprio(1); _Pragma("unroll") for (int m = 0; m < 4; ++m) _Pragma("unroll") for (int n = 0; n < 2; ++n) _Pragma("unroll") for (int k = 0; k < 2; ++k) \
;         acc[ai][bj][m][n] = __builtin_amdgcn_mfma_f32_16x16x32_bf16(Bt[n][k], At[m][k], acc[ai][bj][m][n], 0, 0, 0); __builtin_amdgcn_s_setprio(0); } while (0)
; #define G_WAIT_V(n) asm volatile("s_waitcnt vmcnt(" #n ")" ::: "memory")
; #define G_WAIT_L(n) asm volatile("s_waitcnt lgkmcnt(" #n ")" ::: "memory")
; #define G_BAR __builtin_amdgcn_s_barrier()
; #define G_SCHED __builtin_amdgcn_sched_barrier(0)
; template <class J>
; DI void gemm_phase(LAS unsigned char* lds, const J& job) {
;     ...
;       G_WAIT_V(6); G_BAR; G_MMA(1, 1, At, B1); G_BAR;
;       G_LDB(B0, 1, 0); G_SCHED; G_LDA(At, 1, 0); G_STAGE(G_SA(0, 1), a2 + hstepA, voffA);
;       G_WAIT_L(8); G_BAR; G_WAIT_L(0); G_MMA(0, 0, At, B0); G_BAR; G_SCHED;
;       G_LDB(B1, 1, 1); G_STAGE(G_SB(1, 0), b3, voffB);
;       G_BAR; G_WAIT_L(0); G_MMA(0, 1, At, B1); G_BAR;
	v_mfma_f32_16x16x32_bf16 v[52:55], v[192:195], v[160:163], v[52:55]
	v_mfma_f32_16x16x32_bf16 v[48:51], v[200:203], v[160:163], v[48:51]
	v_mfma_f32_16x16x32_bf16 v[36:39], v[192:195], v[168:171], v[36:39]
	v_mfma_f32_16x16x32_bf16 v[32:35], v[200:203], v[168:171], v[32:35]
	v_mfma_f32_16x16x32_bf16 v[20:23], v[192:195], v[176:179], v[20:23]
	v_mfma_f32_16x16x32_bf16 v[16:19], v[200:203], v[176:179], v[16:19]
	v_mfma_f32_16x16x32_bf16 v[4:7], v[192:195], v[184:187], v[4:7]
	v_mfma_f32_16x16x32_bf16 v[0:3], v[200:203], v[184:187], v[0:3]
	v_mfma_f32_16x16x32_bf16 v[52:55], v[196:199], v[164:167], v[52:55]
	v_mfma_f32_16x16x32_bf16 v[48:51], v[204:207], v[164:167], v[48:51]
	v_mfma_f32_16x16x32_bf16 v[36:39], v[196:199], v[172:175], v[36:39]
	v_mfma_f32_16x16x32_bf16 v[32:35], v[204:207], v[172:175], v[32:35]
	v_mfma_f32_16x16x32_bf16 v[20:23], v[196:199], v[180:183], v[20:23]
	v_mfma_f32_16x16x32_bf16 v[16:19], v[204:207], v[180:183], v[16:19]
	v_mfma_f32_16x16x32_bf16 v[4:7], v[196:199], v[188:191], v[4:7]
	v_mfma_f32_16x16x32_bf16 v[0:3], v[204:207], v[188:191], v[0:3]
	s_add_i32 s0, s88, 0x100
	s_barrier
	ds_read_b128 v[134:137], v208 offset:32768
	ds_read_b128 v[138:141], v208 offset:33792
	ds_read_b128 v[152:155], v208 offset:34816
	ds_read_b128 v[156:159], v208 offset:35840
	s_add_u32 s10, s74, 0x80000
	s_addc_u32 s11, s75, 0
	s_mov_b32 m0, s25
	ds_read_b128 v[160:163], v151 offset:32768
	ds_read_b128 v[164:167], v151 offset:33792
	ds_read_b128 v[168:171], v151 offset:34816
	ds_read_b128 v[172:175], v151 offset:35840
	ds_read_b128 v[176:179], v151 offset:36864
	ds_read_b128 v[180:183], v151 offset:37888
	ds_read_b128 v[184:187], v151 offset:38912
	ds_read_b128 v[188:191], v151 offset:39936
	global_load_lds_dwordx4 v128, s[10:11]
	s_mov_b32 m0, s36
	s_nop 0
	global_load_lds_dwordx4 v130, s[10:11]
	s_waitcnt lgkmcnt(8)
	s_barrier
	s_waitcnt lgkmcnt(0)
	v_mfma_f32_16x16x32_bf16 v[124:127], v[134:137], v[160:163], v[124:127]
	v_mfma_f32_16x16x32_bf16 v[120:123], v[152:155], v[160:163], v[120:123]
	v_mfma_f32_16x16x32_bf16 v[108:111], v[134:137], v[168:171], v[108:111]
	v_mfma_f32_16x16x32_bf16 v[104:107], v[152:155], v[168:171], v[104:107]
	v_mfma_f32_16x16x32_bf16 v[92:95], v[134:137], v[176:179], v[92:95]
	v_mfma_f32_16x16x32_bf16 v[88:91], v[152:155], v[176:179], v[88:91]
	v_mfma_f32_16x16x32_bf16 v[76:79], v[134:137], v[184:187], v[76:79]
	v_mfma_f32_16x16x32_bf16 v[72:75], v[152:155], v[184:187], v[72:75]
	v_mfma_f32_16x16x32_bf16 v[124:127], v[138:141], v[164:167], v[124:127]
	v_mfma_f32_16x16x32_bf16 v[120:123], v[156:159], v[164:167], v[120:123]
	v_mfma_f32_16x16x32_bf16 v[108:111], v[138:141], v[172:175], v[108:111]
	v_mfma_f32_16x16x32_bf16 v[104:107], v[156:159], v[172:175], v[104:107]
	v_mfma_f32_16x16x32_bf16 v[92:95], v[138:141], v[180:183], v[92:95]
	v_mfma_f32_16x16x32_bf16 v[88:91], v[156:159], v[180:183], v[88:91]
	v_mfma_f32_16x16x32_bf16 v[76:79], v[138:141], v[188:191], v[76:79]
	v_mfma_f32_16x16x32_bf16 v[72:75], v[156:159], v[188:191], v[72:75]
	s_barrier
	s_add_i32 s1, s89, 0x100
	s_add_i32 s0, s0, s5
	ds_read_b128 v[192:195], v208 offset:49152
	ds_read_b128 v[196:199], v208 offset:50176
	ds_read_b128 v[200:203], v208 offset:51200
	ds_read_b128 v[204:207], v208 offset:52224
	s_mov_b32 m0, s0
	s_nop 0
	global_load_lds_dwordx4 v146, s[70:71]
	s_add_i32 m0, s0, 0x2000
	s_nop 0
	global_load_lds_dwordx4 v132, s[70:71]
	s_barrier
	s_waitcnt lgkmcnt(0)
	v_mfma_f32_16x16x32_bf16 v[116:119], v[192:195], v[160:163], v[116:119]
	v_mfma_f32_16x16x32_bf16 v[112:115], v[200:203], v[160:163], v[112:115]
	v_mfma_f32_16x16x32_bf16 v[100:103], v[192:195], v[168:171], v[100:103]
	v_mfma_f32_16x16x32_bf16 v[96:99], v[200:203], v[168:171], v[96:99]
	v_mfma_f32_16x16x32_bf16 v[84:87], v[192:195], v[176:179], v[84:87]
	v_mfma_f32_16x16x32_bf16 v[80:83], v[200:203], v[176:179], v[80:83]
	v_mfma_f32_16x16x32_bf16 v[68:71], v[192:195], v[184:187], v[68:71]
	v_mfma_f32_16x16x32_bf16 v[64:67], v[200:203], v[184:187], v[64:67]
	v_mfma_f32_16x16x32_bf16 v[116:119], v[196:199], v[164:167], v[116:119]
	v_mfma_f32_16x16x32_bf16 v[112:115], v[204:207], v[164:167], v[112:115]
	v_mfma_f32_16x16x32_bf16 v[100:103], v[196:199], v[172:175], v[100:103]
	v_mfma_f32_16x16x32_bf16 v[96:99], v[204:207], v[172:175], v[96:99]
	v_mfma_f32_16x16x32_bf16 v[84:87], v[196:199], v[180:183], v[84:87]
	v_mfma_f32_16x16x32_bf16 v[80:83], v[204:207], v[180:183], v[80:83]
	v_mfma_f32_16x16x32_bf16 v[68:71], v[196:199], v[188:191], v[68:71]
	v_mfma_f32_16x16x32_bf16 v[64:67], v[204:207], v[188:191], v[64:67]
	s_mov_b32 m0, s45
	s_barrier
; #define G_WAIT_V(n) asm volatile("s_waitcnt vmcnt(" #n ")" ::: "memory")
; template <class J>
; DI void gemm_phase(LAS unsigned char* lds, const J& job) {
;     ...
;     for (int t = 0; t < nt; t += 2) {
;       const bool last = (t == nt - 2);
;       const char* a1 = cA + G_KT(t + 1);
;       const char* a2 = last ? nA + G_KT(0) : cA + G_KT(t + 2); const char* b2 = last ? nB + G_KT(0) : cB + G_KT(t + 2);
;       const char* a3 = last ? nA + G_KT(1) : cA + G_KT(t + 3); const char* b3 = last ? nB + G_KT(1) : cB + G_KT(t + 3);
;       G_LDB(B0, 0, 0); G_SCHED; G_LDA(At, 0, 0); G_STAGE(G_SA(1, 1), a1 + hstepA, voffA);
;       G_WAIT_L(8); G_BAR; G_WAIT_L(0); G_MMA(0, 0, At, B0); G_BAR; G_SCHED;
;       G_LDB(B1, 0, 1); G_STAGE(G_SB(0, 0), b2, voffB);
;       G_BAR; G_WAIT_L(0); G_MMA(0, 1, At, B1); G_BAR;
;       G_LDA(At, 0, 1); G_STAGE(G_SA(0, 0), a2, voffA);
;       G_BAR; G_WAIT_L(0); G_MMA(1, 0, At, B0); G_BAR; G_SCHED;
;       G_STAGE(G_SB(0, 1), b2 + hstepB, voffB);
;       G_WAIT_V(6); G_BAR; G_MMA(1, 1, At, B1); G_BAR;
;       G_LDB(B0, 1, 0); G_SCHED; G_LDA(At, 1, 0); G_STAGE(G_SA(0, 1), a2 + hstepA, voffA);
;       G_WAIT_L(8); G_BAR; G_WAIT_L(0); G_MMA(0, 0, At, B0); G_BAR; G_SCHED;
;       G_LDB(B1, 1, 1); G_STAGE(G_SB(1, 0), b3, voffB);
;       G_BAR; G_WAIT_L(0); G_MMA(0, 1, At, B1); G_BAR;
;       G_LDA(At, 1, 1); G_STAGE(G_SA(1, 0), a3, voffA);
;       G_BAR; G_WAIT_L(0); G_MMA(1, 0, At, B0); G_BAR; G_SCHED;
;       G_STAGE(G_SB(1, 1), b3 + hstepB, voffB);
;       G_WAIT_V(6); G_BAR; G_MMA(1, 1, At, B1); G_BAR;
;   DI void epi(const Acc& acc, const Unit& u, int wr, int wc, int fr, int fq) const {
;     ...
;         const int rl = ai * HALF + wr * 64 + m * 16 + fr;
; #pragma unroll
;         for (int bj = 0; bj < 2; ++bj) {
;           const int col = u.pn * 256 + bj * HALF + wc * 32 + 8 * fq;
;           const f32x4 v0 = acc[ai][bj][m][0], v1 = acc[ai][bj][m][1];
;           const int row = u.pm * 256 + rl;
;           u32x4 o; o.x = pk2(v0.x, v0.y); o.y = pk2(v0.z, v0.w); o.z = pk2(v1.x, v1.y); o.w = pk2(v1.z, v1.w);
;           *(u32x4*)(proj + (size_t)row * NPROJ + col) = o;
;           if (u.pn >= 8 && u.pn < 12) {
;             const int isv = u.pn >= 10; const int cc = col - (isv ? C_BV : C_BK);
;             float* dst = out + (isv ? O_VP : O_KP) + ((size_t)l * TP + row) * 512 + cc;
;             *(f32x4*)dst = v0; *(f32x4*)(dst + 4) = v1;
	ds_read_b128 v[160:163], v151 offset:49152
	ds_read_b128 v[164:167], v151 offset:50176
	ds_read_b128 v[168:171], v151 offset:51200
	ds_read_b128 v[172:175], v151 offset:52224
	ds_read_b128 v[176:179], v151 offset:53248
	ds_read_b128 v[180:183], v151 offset:54272
	ds_read_b128 v[184:187], v151 offset:55296
	ds_read_b128 v[188:191], v151 offset:56320
	global_load_lds_dwordx4 v128, s[72:73]
	s_mov_b32 m0, s65
	s_nop 0
	global_load_lds_dwordx4 v130, s[72:73]
	s_barrier
	s_waitcnt lgkmcnt(0)
	v_mfma_f32_16x16x32_bf16 v[60:63], v[134:137], v[160:163], v[60:63]
	v_mfma_f32_16x16x32_bf16 v[56:59], v[152:155], v[160:163], v[56:59]
	v_mfma_f32_16x16x32_bf16 v[44:47], v[134:137], v[168:171], v[44:47]
	v_mfma_f32_16x16x32_bf16 v[40:43], v[152:155], v[168:171], v[40:43]
	v_mfma_f32_16x16x32_bf16 v[28:31], v[134:137], v[176:179], v[28:31]
	v_mfma_f32_16x16x32_bf16 v[24:27], v[152:155], v[176:179], v[24:27]
	v_mfma_f32_16x16x32_bf16 v[12:15], v[134:137], v[184:187], v[12:15]
	v_mfma_f32_16x16x32_bf16 v[8:11], v[152:155], v[184:187], v[8:11]
	v_mfma_f32_16x16x32_bf16 v[60:63], v[138:141], v[164:167], v[60:63]
	v_mfma_f32_16x16x32_bf16 v[56:59], v[156:159], v[164:167], v[56:59]
	v_mfma_f32_16x16x32_bf16 v[44:47], v[138:141], v[172:175], v[44:47]
	v_mfma_f32_16x16x32_bf16 v[40:43], v[156:159], v[172:175], v[40:43]
	v_mfma_f32_16x16x32_bf16 v[28:31], v[138:141], v[180:183], v[28:31]
	v_mfma_f32_16x16x32_bf16 v[24:27], v[156:159], v[180:183], v[24:27]
	v_mfma_f32_16x16x32_bf16 v[12:15], v[138:141], v[188:191], v[12:15]
	v_mfma_f32_16x16x32_bf16 v[8:11], v[156:159], v[188:191], v[8:11]
	s_barrier
	s_add_u32 s10, s70, 0x80000
	s_addc_u32 s11, s71, 0
	s_add_i32 s0, s1, s5
	s_mov_b32 m0, s0
	s_nop 0
	global_load_lds_dwordx4 v146, s[10:11]
	s_add_i32 m0, s0, 0x2000
	s_nop 0
	global_load_lds_dwordx4 v132, s[10:11]
	s_add_i32 s6, s6, 2
	s_addk_i32 s56, 0x100
	s_addk_i32 s7, 0x100
	s_add_i32 s1, s56, 0xffffff80
	s_and_b32 s0, s7, 0xf80
	s_and_b32 s1, s1, 0xf00
	s_add_u32 s10, s68, s1
	s_addc_u32 s11, s69, 0
	s_add_u32 s1, s66, s1
	s_addc_u32 s57, s67, 0
	s_and_b32 s70, s56, 0xf80
	s_add_u32 s71, s68, s70
	s_addc_u32 s72, s69, 0
	s_add_u32 s70, s66, s70
	s_addc_u32 s80, s67, 0
	s_cmp_eq_u32 s6, 28
	s_cselect_b32 s75, s46, s11
	s_cselect_b32 s74, s21, s10
	s_cselect_b32 s77, s96, s57
	s_cselect_b32 s76, s47, s1
	s_cselect_b32 s73, s97, s72
	s_cselect_b32 s72, s33, s71
	s_cselect_b32 s71, vcc_hi, s80
	s_cselect_b32 s70, vcc_lo, s70
	s_add_i32 s1, s84, 0x100
	s_add_u32 s10, s9, s0
	s_addc_u32 s11, s19, 0
	s_waitcnt vmcnt(6)
	s_barrier
	v_mfma_f32_16x16x32_bf16 v[52:55], v[192:195], v[160:163], v[52:55]
	v_mfma_f32_16x16x32_bf16 v[48:51], v[200:203], v[160:163], v[48:51]
	v_mfma_f32_16x16x32_bf16 v[36:39], v[192:195], v[168:171], v[36:39]
	v_mfma_f32_16x16x32_bf16 v[32:35], v[200:203], v[168:171], v[32:35]
	v_mfma_f32_16x16x32_bf16 v[20:23], v[192:195], v[176:179], v[20:23]
	v_mfma_f32_16x16x32_bf16 v[16:19], v[200:203], v[176:179], v[16:19]
	v_mfma_f32_16x16x32_bf16 v[4:7], v[192:195], v[184:187], v[4:7]
	v_mfma_f32_16x16x32_bf16 v[0:3], v[200:203], v[184:187], v[0:3]
	v_mfma_f32_16x16x32_bf16 v[52:55], v[196:199], v[164:167], v[52:55]
	v_mfma_f32_16x16x32_bf16 v[48:51], v[204:207], v[164:167], v[48:51]
	v_mfma_f32_16x16x32_bf16 v[36:39], v[196:199], v[172:175], v[36:39]
	v_mfma_f32_16x16x32_bf16 v[32:35], v[204:207], v[172:175], v[32:35]
	v_mfma_f32_16x16x32_bf16 v[20:23], v[196:199], v[180:183], v[20:23]
	v_mfma_f32_16x16x32_bf16 v[16:19], v[204:207], v[180:183], v[16:19]
	v_mfma_f32_16x16x32_bf16 v[4:7], v[196:199], v[188:191], v[4:7]
	v_mfma_f32_16x16x32_bf16 v[0:3], v[204:207], v[188:191], v[0:3]
	s_cmp_gt_u32 s6, 29
	s_barrier
	s_cbranch_scc0 .LBB0_282
	v_mov_b32_e32 v135, v148
	v_mov_b32_e32 v134, v149
	s_lshl_b32 s0, s64, 8
	s_or_b32 s0, s0, s38
	v_lshl_add_u32 v134, v134, 3, s0
	s_lshl_b32 s0, s8, 8
	s_add_i32 s0, s0, s37
	v_add_u32_e32 v136, s0, v135
	s_and_b32 s0, s64, -4
	s_cmp_eq_u32 s0, 8
	s_cselect_b64 s[66:67], -1, 0
	s_cmp_gt_u32 s64, 9
	s_cselect_b64 s[6:7], -1, 0
	s_and_b64 s[6:7], s[6:7], exec
	s_movk_i32 s1, 0xf600
	v_mov_b64_e32 v[138:139], s[26:27]
	s_cselect_b32 s7, s1, 0xfffff800
	s_mov_b32 s1, 0x3040000
	v_ashrrev_i32_e32 v137, 31, v136
	v_mad_i64_i32 v[138:139], s[8:9], v136, s92, v[138:139]
	v_ashrrev_i32_e32 v135, 31, v134
	s_cselect_b32 s6, s1, 0x2040000
	s_cmp_lg_u32 s0, 8
	v_lshlrev_b64 v[140:141], 11, v[136:137]
	v_lshl_add_u64 v[142:143], v[134:135], 1, v[138:139]
	v_add_u32_e32 v138, s7, v134
	v_cvt_pk_bf16_f32 v152, v124, v125
	v_cvt_pk_bf16_f32 v153, v126, v127
	v_cvt_pk_bf16_f32 v154, v120, v121
	v_cvt_pk_bf16_f32 v155, v122, v123
	global_store_dwordx4 v[142:143], v[152:155], off
	s_cbranch_scc1 .LBB0_285
	s_lshl_b32 s0, s6, 2
	s_add_u32 s8, s83, s0
	s_addc_u32 s9, s86, 0
	v_lshl_add_u64 v[152:153], s[8:9], 0, v[140:141]
	v_ashrrev_i32_e32 v139, 31, v138
	v_lshl_add_u64 v[152:153], v[138:139], 2, v[152:153]
	global_store_dwordx4 v[152:153], v[124:127], off
	global_store_dwordx4 v[152:153], v[120:123], off offset:16
